# speedup vs baseline: 1.0007x; 1.0007x over previous
; #define PG8_STAGE(bufoff, gbase, voff) do { _Pragma("unroll") for (int _i = 0; _i < 2; ++_i) \
;         __builtin_amdgcn_global_load_lds((const unsigned*)((const char*)(gbase) + (voff)[_i]), (PG8_LAS unsigned*)(lds + (bufoff) + ldsw + _i * 8192), 16, 0, 0); } while (0)
; #define PG8_WAIT_V(n) asm volatile("s_waitcnt vmcnt(" #n ")" ::: "memory")
; #define PG8_WAIT_L(n) asm volatile("s_waitcnt lgkmcnt(" #n ")" ::: "memory")
; #define PG8_BAR __builtin_amdgcn_s_barrier()
; #define PG8_SCHED __builtin_amdgcn_sched_barrier(0)
; template <class Epi, class Sched, bool ALIGN_EPI = false, bool SP2 = false, bool FP8 = false>
; __device__ __forceinline__ void gemm_phase(PG8_LAS unsigned char* lds, const Gemm g, const Sched& S, const Epi& E, const int tid) {
;     ...
;             PG8_WAIT_V(8); PG8_WAIT_L(0); PG8_BAR; PG8_MMA(0, 0, At, B0); PG8_MMA(0, 1, At, B1); PG8_BAR; PG8_SCHED;
;             PG8_LDA(At, 0, 1); PG8_STAGE(PG8_SB(0, 0), b2, voffB); PG8_STAGE(PG8_SB(0, 1), b2 + hstepB, voffB); PG8_STAGE(PG8_SA(0, 0), a2, voffA);
;             PG8_WAIT_V(8); PG8_WAIT_L(0); PG8_BAR; PG8_MMA(1, 0, At, B0); PG8_MMA(1, 1, At, B1); PG8_BAR; PG8_SCHED;
.Lskw_0_0:
	s_waitcnt lgkmcnt(0)
	s_barrier
	s_setprio 0
	s_waitcnt lgkmcnt(0)
	v_mfma_f32_16x16x32_bf16 v[126:129], v[142:145], v[196:199], v[126:129]
	v_mfma_f32_16x16x32_bf16 v[122:125], v[154:157], v[196:199], v[122:125]
	v_mfma_f32_16x16x32_bf16 v[110:113], v[142:145], v[224:227], v[110:113]
	v_mfma_f32_16x16x32_bf16 v[106:109], v[154:157], v[224:227], v[106:109]
	v_mfma_f32_16x16x32_bf16 v[94:97], v[142:145], v[232:235], v[94:97]
	v_mfma_f32_16x16x32_bf16 v[90:93], v[154:157], v[232:235], v[90:93]
	v_mfma_f32_16x16x32_bf16 v[78:81], v[142:145], v[240:243], v[78:81]
	v_mfma_f32_16x16x32_bf16 v[74:77], v[154:157], v[240:243], v[74:77]
	v_mfma_f32_16x16x32_bf16 v[126:129], v[146:149], v[220:223], v[126:129]
	v_mfma_f32_16x16x32_bf16 v[122:125], v[158:161], v[220:223], v[122:125]
	v_mfma_f32_16x16x32_bf16 v[110:113], v[146:149], v[228:231], v[110:113]
	v_mfma_f32_16x16x32_bf16 v[106:109], v[158:161], v[228:231], v[106:109]
	v_mfma_f32_16x16x32_bf16 v[94:97], v[146:149], v[236:239], v[94:97]
	v_mfma_f32_16x16x32_bf16 v[90:93], v[158:161], v[236:239], v[90:93]
	v_mfma_f32_16x16x32_bf16 v[78:81], v[146:149], v[244:247], v[78:81]
	v_mfma_f32_16x16x32_bf16 v[74:77], v[158:161], v[244:247], v[74:77]
	s_setprio 1
	s_setprio 0
	v_mfma_f32_16x16x32_bf16 v[118:121], v[180:183], v[196:199], v[118:121]
	v_mfma_f32_16x16x32_bf16 v[114:117], v[188:191], v[196:199], v[114:117]
	v_mfma_f32_16x16x32_bf16 v[102:105], v[180:183], v[224:227], v[102:105]
	v_mfma_f32_16x16x32_bf16 v[98:101], v[188:191], v[224:227], v[98:101]
	v_mfma_f32_16x16x32_bf16 v[86:89], v[180:183], v[232:235], v[86:89]
	v_mfma_f32_16x16x32_bf16 v[82:85], v[188:191], v[232:235], v[82:85]
	v_mfma_f32_16x16x32_bf16 v[70:73], v[180:183], v[240:243], v[70:73]
	v_mfma_f32_16x16x32_bf16 v[66:69], v[188:191], v[240:243], v[66:69]
	v_mfma_f32_16x16x32_bf16 v[118:121], v[184:187], v[220:223], v[118:121]
	v_mfma_f32_16x16x32_bf16 v[114:117], v[192:195], v[220:223], v[114:117]
	v_mfma_f32_16x16x32_bf16 v[102:105], v[184:187], v[228:231], v[102:105]
	v_mfma_f32_16x16x32_bf16 v[98:101], v[192:195], v[228:231], v[98:101]
	v_mfma_f32_16x16x32_bf16 v[86:89], v[184:187], v[236:239], v[86:89]
	v_mfma_f32_16x16x32_bf16 v[82:85], v[192:195], v[236:239], v[82:85]
	v_mfma_f32_16x16x32_bf16 v[70:73], v[184:187], v[244:247], v[70:73]
	v_mfma_f32_16x16x32_bf16 v[66:69], v[192:195], v[244:247], v[66:69]
	s_setprio 1
	s_barrier
	s_add_i32 s57, s57, s42
	v_lshl_add_u64 v[200:201], s[36:37], 0, v[134:135]
	s_mov_b32 m0, s57
	ds_read_b128 v[196:199], v152 offset:16384
	ds_read_b128 v[220:223], v152 offset:17408
	ds_read_b128 v[224:227], v152 offset:18432
	ds_read_b128 v[228:231], v152 offset:19456
	ds_read_b128 v[232:235], v152 offset:20480
	ds_read_b128 v[236:239], v152 offset:21504
	ds_read_b128 v[240:243], v152 offset:22528
	ds_read_b128 v[244:247], v152 offset:23552
	global_load_lds_dwordx4 v[200:201], off
	s_add_i32 m0, s57, 0x2000
	s_add_u32 s58, s36, 0x80000
	v_lshl_add_u64 v[248:249], s[36:37], 0, v[130:131]
	s_addc_u32 s59, s37, 0
	s_add_i32 s57, s60, s42
	global_load_lds_dwordx4 v[248:249], off
	v_lshl_add_u64 v[250:251], s[58:59], 0, v[134:135]
	s_mov_b32 m0, s57
	v_lshl_add_u64 v[164:165], s[40:41], 0, v[132:133]
	global_load_lds_dwordx4 v[250:251], off
	v_lshl_add_u64 v[250:251], s[58:59], 0, v[130:131]
	s_add_i32 m0, s57, 0x2000
	s_nop 0
	global_load_lds_dwordx4 v[250:251], off
	v_lshl_add_u64 v[250:251], s[40:41], 0, v[136:137]
	s_mov_b32 m0, s43
	s_nop 0
	global_load_lds_dwordx4 v[250:251], off
	s_mov_b32 m0, s44
	s_nop 0
	global_load_lds_dwordx4 v[164:165], off
	s_cmp_eq_i32 s56, -2
	s_cbranch_scc1 .Lskw_0_1
	s_waitcnt vmcnt(8)
.Lskw_0_1:
	s_waitcnt lgkmcnt(0)
	s_barrier
	s_setprio 0
	s_waitcnt lgkmcnt(0)
	v_mfma_f32_16x16x32_bf16 v[62:65], v[142:145], v[196:199], v[62:65]
	v_mfma_f32_16x16x32_bf16 v[58:61], v[154:157], v[196:199], v[58:61]
	v_mfma_f32_16x16x32_bf16 v[46:49], v[142:145], v[224:227], v[46:49]
	v_mfma_f32_16x16x32_bf16 v[42:45], v[154:157], v[224:227], v[42:45]
	v_mfma_f32_16x16x32_bf16 v[28:31], v[142:145], v[232:235], v[28:31]
	v_mfma_f32_16x16x32_bf16 v[24:27], v[154:157], v[232:235], v[24:27]
	v_mfma_f32_16x16x32_bf16 v[12:15], v[142:145], v[240:243], v[12:15]
	v_mfma_f32_16x16x32_bf16 v[8:11], v[154:157], v[240:243], v[8:11]
	v_mfma_f32_16x16x32_bf16 v[62:65], v[146:149], v[220:223], v[62:65]
	v_mfma_f32_16x16x32_bf16 v[58:61], v[158:161], v[220:223], v[58:61]
	v_mfma_f32_16x16x32_bf16 v[46:49], v[146:149], v[228:231], v[46:49]
	v_mfma_f32_16x16x32_bf16 v[42:45], v[158:161], v[228:231], v[42:45]
	v_mfma_f32_16x16x32_bf16 v[28:31], v[146:149], v[236:239], v[28:31]
	v_mfma_f32_16x16x32_bf16 v[24:27], v[158:161], v[236:239], v[24:27]
	v_mfma_f32_16x16x32_bf16 v[12:15], v[146:149], v[244:247], v[12:15]
	v_mfma_f32_16x16x32_bf16 v[8:11], v[158:161], v[244:247], v[8:11]
	s_setprio 1
	s_setprio 0
	v_mfma_f32_16x16x32_bf16 v[54:57], v[180:183], v[196:199], v[54:57]
	v_mfma_f32_16x16x32_bf16 v[50:53], v[188:191], v[196:199], v[50:53]
	v_mfma_f32_16x16x32_bf16 v[38:41], v[180:183], v[224:227], v[38:41]
	v_mfma_f32_16x16x32_bf16 v[34:37], v[188:191], v[224:227], v[34:37]
	v_mfma_f32_16x16x32_bf16 v[20:23], v[180:183], v[232:235], v[20:23]
	v_mfma_f32_16x16x32_bf16 v[16:19], v[188:191], v[232:235], v[16:19]
	v_mfma_f32_16x16x32_bf16 v[4:7], v[180:183], v[240:243], v[4:7]
	v_mfma_f32_16x16x32_bf16 v[0:3], v[188:191], v[240:243], v[0:3]
	v_mfma_f32_16x16x32_bf16 v[54:57], v[184:187], v[220:223], v[54:57]
	v_mfma_f32_16x16x32_bf16 v[50:53], v[192:195], v[220:223], v[50:53]
	v_mfma_f32_16x16x32_bf16 v[38:41], v[184:187], v[228:231], v[38:41]
	v_mfma_f32_16x16x32_bf16 v[34:37], v[192:195], v[228:231], v[34:37]
	v_mfma_f32_16x16x32_bf16 v[20:23], v[184:187], v[236:239], v[20:23]
	v_mfma_f32_16x16x32_bf16 v[16:19], v[192:195], v[236:239], v[16:19]
	v_mfma_f32_16x16x32_bf16 v[4:7], v[184:187], v[244:247], v[4:7]
	v_mfma_f32_16x16x32_bf16 v[0:3], v[192:195], v[244:247], v[0:3]
	s_setprio 1
	s_barrier
; #define PG8_STAGE(bufoff, gbase, voff) do { _Pragma("unroll") for (int _i = 0; _i < 2; ++_i) \
;         __builtin_amdgcn_global_load_lds((const unsigned*)((const char*)(gbase) + (voff)[_i]), (PG8_LAS unsigned*)(lds + (bufoff) + ldsw + _i * 8192), 16, 0, 0); } while (0)
; #define PG8_WAIT_V(n) asm volatile("s_waitcnt vmcnt(" #n ")" ::: "memory")
; #define PG8_WAIT_L(n) asm volatile("s_waitcnt lgkmcnt(" #n ")" ::: "memory")
; #define PG8_BAR __builtin_amdgcn_s_barrier()
; #define PG8_SCHED __builtin_amdgcn_sched_barrier(0)
; template <class Epi, class Sched, bool ALIGN_EPI = false, bool SP2 = false, bool FP8 = false>
; __device__ __forceinline__ void gemm_phase(PG8_LAS unsigned char* lds, const Gemm g, const Sched& S, const Epi& E, const int tid) {
;     ...
;             PG8_LDB(B0, 1, 0); PG8_LDB(B1, 1, 1); PG8_SCHED; PG8_LDA(At, 1, 0); PG8_STAGE(PG8_SA(0, 1), a2 + hstepA, voffA);
;             PG8_WAIT_V(8); PG8_WAIT_L(0); PG8_BAR; PG8_MMA(0, 0, At, B0); PG8_MMA(0, 1, At, B1); PG8_BAR; PG8_SCHED;
	s_add_i32 s57, 0, 0x18000
	v_add_u32_e32 v153, s57, v150
	s_add_i32 s58, 0, 0x1c000
	ds_read_b128 v[142:145], v153
	ds_read_b128 v[146:149], v153 offset:1024
	ds_read_b128 v[154:157], v153 offset:2048
	ds_read_b128 v[158:161], v153 offset:3072
	v_add_u32_e32 v153, s58, v150
	ds_read_b128 v[180:183], v153
	ds_read_b128 v[184:187], v153 offset:1024
	ds_read_b128 v[188:191], v153 offset:2048
	ds_read_b128 v[192:195], v153 offset:3072
	s_add_u32 s40, s40, 0x80000
	s_addc_u32 s41, s41, 0
	s_mov_b32 m0, s45
	v_lshl_add_u64 v[166:167], s[40:41], 0, v[136:137]
	ds_read_b128 v[196:199], v152 offset:32768
	ds_read_b128 v[220:223], v152 offset:33792
	ds_read_b128 v[224:227], v152 offset:34816
	ds_read_b128 v[228:231], v152 offset:35840
	ds_read_b128 v[232:235], v152 offset:36864
	ds_read_b128 v[236:239], v152 offset:37888
	ds_read_b128 v[240:243], v152 offset:38912
	ds_read_b128 v[244:247], v152 offset:39936
	global_load_lds_dwordx4 v[166:167], off
	v_lshl_add_u64 v[166:167], s[40:41], 0, v[132:133]
	s_mov_b32 m0, s46
	s_nop 0
	global_load_lds_dwordx4 v[166:167], off
	s_waitcnt vmcnt(8)
	s_waitcnt lgkmcnt(0)
	s_barrier
	s_setprio 0
	s_waitcnt lgkmcnt(0)
	v_mfma_f32_16x16x32_bf16 v[126:129], v[142:145], v[196:199], v[126:129]
	v_mfma_f32_16x16x32_bf16 v[122:125], v[154:157], v[196:199], v[122:125]
	v_mfma_f32_16x16x32_bf16 v[110:113], v[142:145], v[224:227], v[110:113]
	v_mfma_f32_16x16x32_bf16 v[106:109], v[154:157], v[224:227], v[106:109]
	v_mfma_f32_16x16x32_bf16 v[94:97], v[142:145], v[232:235], v[94:97]
	v_mfma_f32_16x16x32_bf16 v[90:93], v[154:157], v[232:235], v[90:93]
	v_mfma_f32_16x16x32_bf16 v[78:81], v[142:145], v[240:243], v[78:81]
	v_mfma_f32_16x16x32_bf16 v[74:77], v[154:157], v[240:243], v[74:77]
	v_mfma_f32_16x16x32_bf16 v[126:129], v[146:149], v[220:223], v[126:129]
	v_mfma_f32_16x16x32_bf16 v[122:125], v[158:161], v[220:223], v[122:125]
	v_mfma_f32_16x16x32_bf16 v[110:113], v[146:149], v[228:231], v[110:113]
	v_mfma_f32_16x16x32_bf16 v[106:109], v[158:161], v[228:231], v[106:109]
	v_mfma_f32_16x16x32_bf16 v[94:97], v[146:149], v[236:239], v[94:97]
	v_mfma_f32_16x16x32_bf16 v[90:93], v[158:161], v[236:239], v[90:93]
	v_mfma_f32_16x16x32_bf16 v[78:81], v[146:149], v[244:247], v[78:81]
	v_mfma_f32_16x16x32_bf16 v[74:77], v[158:161], v[244:247], v[74:77]
	s_setprio 1
	s_setprio 0
	v_mfma_f32_16x16x32_bf16 v[118:121], v[180:183], v[196:199], v[118:121]
	v_mfma_f32_16x16x32_bf16 v[114:117], v[188:191], v[196:199], v[114:117]
	v_mfma_f32_16x16x32_bf16 v[102:105], v[180:183], v[224:227], v[102:105]
	v_mfma_f32_16x16x32_bf16 v[98:101], v[188:191], v[224:227], v[98:101]
	v_mfma_f32_16x16x32_bf16 v[86:89], v[180:183], v[232:235], v[86:89]
	v_mfma_f32_16x16x32_bf16 v[82:85], v[188:191], v[232:235], v[82:85]
	v_mfma_f32_16x16x32_bf16 v[70:73], v[180:183], v[240:243], v[70:73]
	v_mfma_f32_16x16x32_bf16 v[66:69], v[188:191], v[240:243], v[66:69]
	v_mfma_f32_16x16x32_bf16 v[118:121], v[184:187], v[220:223], v[118:121]
	v_mfma_f32_16x16x32_bf16 v[114:117], v[192:195], v[220:223], v[114:117]
	v_mfma_f32_16x16x32_bf16 v[102:105], v[184:187], v[228:231], v[102:105]
	v_mfma_f32_16x16x32_bf16 v[98:101], v[192:195], v[228:231], v[98:101]
	v_mfma_f32_16x16x32_bf16 v[86:89], v[184:187], v[236:239], v[86:89]
	v_mfma_f32_16x16x32_bf16 v[82:85], v[192:195], v[236:239], v[82:85]
	v_mfma_f32_16x16x32_bf16 v[70:73], v[184:187], v[244:247], v[70:73]
	v_mfma_f32_16x16x32_bf16 v[66:69], v[192:195], v[244:247], v[66:69]
	s_setprio 1
	s_barrier
; #define PG8_STAGE(bufoff, gbase, voff) do { _Pragma("unroll") for (int _i = 0; _i < 2; ++_i) \
;         __builtin_amdgcn_global_load_lds((const unsigned*)((const char*)(gbase) + (voff)[_i]), (PG8_LAS unsigned*)(lds + (bufoff) + ldsw + _i * 8192), 16, 0, 0); } while (0)
; #define PG8_WAIT_V(n) asm volatile("s_waitcnt vmcnt(" #n ")" ::: "memory")
; #define PG8_WAIT_L(n) asm volatile("s_waitcnt lgkmcnt(" #n ")" ::: "memory")
; #define PG8_BAR __builtin_amdgcn_s_barrier()
; #define PG8_SCHED __builtin_amdgcn_sched_barrier(0)
;     __device__ __forceinline__ void operator()(const f32x4 (&acc)[2][2][4][2], const Unit& u, int wr, int wc, int fr, int fq) const {
;     ...
;             for (int m = 0; m < 4; ++m) { const int row = row0 + ai * HALF + m * 16; const float rs = __builtin_amdgcn_rsqf((float)ss[row] * (SS_INV / 2048.0f) + RMS_EPS) * osc;
; template <class Epi, class Sched, bool ALIGN_EPI = false, bool SP2 = false, bool FP8 = false>
; __device__ __forceinline__ void gemm_phase(PG8_LAS unsigned char* lds, const Gemm g, const Sched& S, const Epi& E, const int tid) {
;     ...
;             PG8_LDA(At, 1, 1); PG8_STAGE(PG8_SB(1, 0), b3, voffB); PG8_STAGE(PG8_SB(1, 1), b3 + hstepB, voffB); PG8_STAGE(PG8_SA(1, 0), a3, voffA);
;             PG8_WAIT_V(8); PG8_WAIT_L(0); PG8_BAR; PG8_MMA(1, 0, At, B0); PG8_MMA(1, 1, At, B1); PG8_BAR; PG8_SCHED;
	s_add_i32 s40, s57, s42
	v_lshl_add_u64 v[166:167], v[200:201], 0, s[38:39]
	s_mov_b32 m0, s40
	ds_read_b128 v[196:199], v152 offset:49152
	ds_read_b128 v[220:223], v152 offset:50176
	ds_read_b128 v[224:227], v152 offset:51200
	ds_read_b128 v[228:231], v152 offset:52224
	ds_read_b128 v[232:235], v152 offset:53248
	ds_read_b128 v[236:239], v152 offset:54272
	ds_read_b128 v[240:243], v152 offset:55296
	ds_read_b128 v[244:247], v152 offset:56320
	global_load_lds_dwordx4 v[166:167], off
	s_add_i32 m0, s40, 0x2000
	s_add_u32 s36, s36, 0x80080
	v_lshl_add_u64 v[166:167], v[248:249], 0, s[38:39]
	s_addc_u32 s37, s37, 0
	s_add_i32 s40, s58, s42
	global_load_lds_dwordx4 v[166:167], off
	v_lshl_add_u64 v[166:167], s[36:37], 0, v[134:135]
	s_mov_b32 m0, s40
	v_lshl_add_u64 v[164:165], v[164:165], 0, s[38:39]
	global_load_lds_dwordx4 v[166:167], off
	v_lshl_add_u64 v[166:167], s[36:37], 0, v[130:131]
	s_add_i32 m0, s40, 0x2000
	s_nop 0
	global_load_lds_dwordx4 v[166:167], off
	v_lshl_add_u64 v[166:167], v[250:251], 0, s[38:39]
	s_mov_b32 m0, s47
	s_nop 0
	global_load_lds_dwordx4 v[166:167], off
	s_mov_b32 m0, s48
	s_nop 0
	global_load_lds_dwordx4 v[164:165], off
	s_waitcnt vmcnt(8)
	s_waitcnt lgkmcnt(0)
	s_barrier
	s_setprio 0
	s_waitcnt lgkmcnt(0)
	v_mfma_f32_16x16x32_bf16 v[62:65], v[142:145], v[196:199], v[62:65]
	v_mfma_f32_16x16x32_bf16 v[58:61], v[154:157], v[196:199], v[58:61]
	v_mfma_f32_16x16x32_bf16 v[46:49], v[142:145], v[224:227], v[46:49]
	v_mfma_f32_16x16x32_bf16 v[42:45], v[154:157], v[224:227], v[42:45]
	v_mfma_f32_16x16x32_bf16 v[28:31], v[142:145], v[232:235], v[28:31]
	v_mfma_f32_16x16x32_bf16 v[24:27], v[154:157], v[232:235], v[24:27]
	v_mfma_f32_16x16x32_bf16 v[12:15], v[142:145], v[240:243], v[12:15]
	v_mfma_f32_16x16x32_bf16 v[8:11], v[154:157], v[240:243], v[8:11]
	v_mfma_f32_16x16x32_bf16 v[62:65], v[146:149], v[220:223], v[62:65]
	v_mfma_f32_16x16x32_bf16 v[58:61], v[158:161], v[220:223], v[58:61]
	v_mfma_f32_16x16x32_bf16 v[46:49], v[146:149], v[228:231], v[46:49]
	v_mfma_f32_16x16x32_bf16 v[42:45], v[158:161], v[228:231], v[42:45]
	v_mfma_f32_16x16x32_bf16 v[28:31], v[146:149], v[236:239], v[28:31]
	v_mfma_f32_16x16x32_bf16 v[24:27], v[158:161], v[236:239], v[24:27]
	v_mfma_f32_16x16x32_bf16 v[12:15], v[146:149], v[244:247], v[12:15]
	v_mfma_f32_16x16x32_bf16 v[8:11], v[158:161], v[244:247], v[8:11]
	s_setprio 1
	s_setprio 0
	v_mfma_f32_16x16x32_bf16 v[54:57], v[180:183], v[196:199], v[54:57]
	v_mfma_f32_16x16x32_bf16 v[50:53], v[188:191], v[196:199], v[50:53]
	v_mfma_f32_16x16x32_bf16 v[38:41], v[180:183], v[224:227], v[38:41]
	v_mfma_f32_16x16x32_bf16 v[34:37], v[188:191], v[224:227], v[34:37]
	v_mfma_f32_16x16x32_bf16 v[20:23], v[180:183], v[232:235], v[20:23]
	v_mfma_f32_16x16x32_bf16 v[16:19], v[188:191], v[232:235], v[16:19]
	v_mfma_f32_16x16x32_bf16 v[4:7], v[180:183], v[240:243], v[4:7]
	v_mfma_f32_16x16x32_bf16 v[0:3], v[188:191], v[240:243], v[0:3]
	v_mfma_f32_16x16x32_bf16 v[54:57], v[184:187], v[220:223], v[54:57]
	v_mfma_f32_16x16x32_bf16 v[50:53], v[192:195], v[220:223], v[50:53]
	v_mfma_f32_16x16x32_bf16 v[38:41], v[184:187], v[228:231], v[38:41]
	v_mfma_f32_16x16x32_bf16 v[34:37], v[192:195], v[228:231], v[34:37]
	v_mfma_f32_16x16x32_bf16 v[20:23], v[184:187], v[236:239], v[20:23]
	v_mfma_f32_16x16x32_bf16 v[16:19], v[192:195], v[236:239], v[16:19]
	v_mfma_f32_16x16x32_bf16 v[4:7], v[184:187], v[244:247], v[4:7]
	v_mfma_f32_16x16x32_bf16 v[0:3], v[192:195], v[244:247], v[0:3]
	s_setprio 1
	s_barrier
	s_add_i32 s56, s56, 2
	s_add_u32 s34, s34, 0x100
	s_addc_u32 s35, s35, 0
	s_add_u32 s54, s54, 0x100
	s_addc_u32 s55, s55, 0
	s_cmp_gt_u32 s56, 29
	s_cbranch_scc0 .LBB0_98
	s_setprio 0
	v_lshl_add_u32 v142, s51, 8, v33
	v_ashrrev_i32_e32 v143, 31, v142
	v_lshl_add_u64 v[148:149], v[142:143], 3, s[8:9]
	global_load_dwordx2 v[220:221], v[148:149], off
	global_load_dwordx2 v[222:223], v[148:149], off offset:128
	global_load_dwordx2 v[224:225], v[148:149], off offset:256
	global_load_dwordx2 v[226:227], v[148:149], off offset:384
	global_load_dwordx2 v[228:229], v[148:149], off offset:1024
	global_load_dwordx2 v[230:231], v[148:149], off offset:1152
	global_load_dwordx2 v[232:233], v[148:149], off offset:1280
	global_load_dwordx2 v[234:235], v[148:149], off offset:1408
	s_and_b64 vcc, exec, s[16:17]
	s_cbranch_vccz .LBB0_101
	s_barrier

; #define PG8_STAGE(bufoff, gbase, voff) do { _Pragma("unroll") for (int _i = 0; _i < 2; ++_i) \
;         __builtin_amdgcn_global_load_lds((const unsigned*)((const char*)(gbase) + (voff)[_i]), (PG8_LAS unsigned*)(lds + (bufoff) + ldsw + _i * 8192), 16, 0, 0); } while (0)
; #define PG8_WAIT_V(n) asm volatile("s_waitcnt vmcnt(" #n ")" ::: "memory")
; #define PG8_WAIT_L(n) asm volatile("s_waitcnt lgkmcnt(" #n ")" ::: "memory")
; #define PG8_BAR __builtin_amdgcn_s_barrier()
; #define PG8_SCHED __builtin_amdgcn_sched_barrier(0)
; template <class Epi, class Sched, bool ALIGN_EPI = false, bool SP2 = false, bool FP8 = false>
; __device__ __forceinline__ void gemm_phase(PG8_LAS unsigned char* lds, const Gemm g, const Sched& S, const Epi& E, const int tid) {
;     ...
;             PG8_WAIT_V(8); PG8_WAIT_L(0); PG8_BAR; PG8_MMA(0, 0, At, B0); PG8_MMA(0, 1, At, B1); PG8_BAR; PG8_SCHED;
;             PG8_LDA(At, 0, 1); PG8_STAGE(PG8_SB(0, 0), b2, voffB); PG8_STAGE(PG8_SB(0, 1), b2 + hstepB, voffB); PG8_STAGE(PG8_SA(0, 0), a2, voffA);
.Lskw_1_0:
	s_waitcnt lgkmcnt(0)
	s_barrier
	s_setprio 0
	s_waitcnt lgkmcnt(0)
	v_mfma_f32_16x16x128_f8f6f4 v[158:161], v[16:23], v[192:199], v[158:161]
	v_mfma_f32_16x16x128_f8f6f4 v[154:157], v[24:31], v[192:199], v[154:157]
	v_mfma_f32_16x16x128_f8f6f4 v[142:145], v[16:23], v[220:227], v[142:145]
	v_mfma_f32_16x16x128_f8f6f4 v[138:141], v[24:31], v[220:227], v[138:141]
	v_mfma_f32_16x16x128_f8f6f4 v[126:129], v[16:23], v[228:235], v[126:129]
	v_mfma_f32_16x16x128_f8f6f4 v[122:125], v[24:31], v[228:235], v[122:125]
	v_mfma_f32_16x16x128_f8f6f4 v[110:113], v[16:23], v[236:243], v[110:113]
	v_mfma_f32_16x16x128_f8f6f4 v[106:109], v[24:31], v[236:243], v[106:109]
	s_setprio 1
	s_setprio 0
	v_mfma_f32_16x16x128_f8f6f4 v[150:153], v[0:7], v[192:199], v[150:153]
	v_mfma_f32_16x16x128_f8f6f4 v[146:149], v[8:15], v[192:199], v[146:149]
	v_mfma_f32_16x16x128_f8f6f4 v[134:137], v[0:7], v[220:227], v[134:137]
	v_mfma_f32_16x16x128_f8f6f4 v[130:133], v[8:15], v[220:227], v[130:133]
	v_mfma_f32_16x16x128_f8f6f4 v[118:121], v[0:7], v[228:235], v[118:121]
	v_mfma_f32_16x16x128_f8f6f4 v[114:117], v[8:15], v[228:235], v[114:117]
	v_mfma_f32_16x16x128_f8f6f4 v[102:105], v[0:7], v[236:243], v[102:105]
	v_mfma_f32_16x16x128_f8f6f4 v[98:101], v[8:15], v[236:243], v[98:101]
	s_setprio 1
	s_barrier
	s_add_i32 s55, s55, s44
	v_lshl_add_u64 v[192:193], s[34:35], 0, v[184:185]
	s_mov_b32 m0, s55
	ds_read_b128 v[220:223], v200 offset:16384
	ds_read_b128 v[224:227], v200 offset:17408
	ds_read_b128 v[228:231], v200 offset:18432
	ds_read_b128 v[232:235], v200 offset:19456
	ds_read_b128 v[236:239], v200 offset:20480
	ds_read_b128 v[240:243], v200 offset:21504
	ds_read_b128 v[244:247], v200 offset:22528
	ds_read_b128 v[248:251], v200 offset:23552
	global_load_lds_dwordx4 v[192:193], off
	s_add_i32 m0, s55, 0x2000
	s_add_u32 s58, s34, 0x40000
	v_lshl_add_u64 v[194:195], s[34:35], 0, v[180:181]
	s_addc_u32 s59, s35, 0
	s_add_i32 s55, s56, s44
	global_load_lds_dwordx4 v[194:195], off
	v_lshl_add_u64 v[164:165], s[58:59], 0, v[184:185]
	s_mov_b32 m0, s55
	v_lshl_add_u64 v[196:197], s[36:37], 0, v[186:187]
	global_load_lds_dwordx4 v[164:165], off
	v_lshl_add_u64 v[164:165], s[58:59], 0, v[180:181]
	s_add_i32 m0, s55, 0x2000
	v_lshl_add_u64 v[198:199], s[36:37], 0, v[182:183]
	global_load_lds_dwordx4 v[164:165], off
	s_mov_b32 m0, s45
	s_nop 0
	global_load_lds_dwordx4 v[196:197], off
	s_mov_b32 m0, s46
	s_nop 0
	global_load_lds_dwordx4 v[198:199], off
	s_cmp_eq_i32 s54, -2
	s_cbranch_scc1 .Lskw_1_1
	s_waitcnt vmcnt(8)
; #define PG8_STAGE(bufoff, gbase, voff) do { _Pragma("unroll") for (int _i = 0; _i < 2; ++_i) \
;         __builtin_amdgcn_global_load_lds((const unsigned*)((const char*)(gbase) + (voff)[_i]), (PG8_LAS unsigned*)(lds + (bufoff) + ldsw + _i * 8192), 16, 0, 0); } while (0)
; #define PG8_WAIT_V(n) asm volatile("s_waitcnt vmcnt(" #n ")" ::: "memory")
; #define PG8_WAIT_L(n) asm volatile("s_waitcnt lgkmcnt(" #n ")" ::: "memory")
; #define PG8_BAR __builtin_amdgcn_s_barrier()
; #define PG8_SCHED __builtin_amdgcn_sched_barrier(0)
;     __device__ __forceinline__ void operator()(const f32x4 (&acc)[2][2][4][2], const Unit& u, int wr, int wc, int fr, int fq) const {
;     ...
;             for (int m = 0; m < 4; ++m) { const int row = row0 + ai * HALF + m * 16; const float rs = __builtin_amdgcn_rsqf((float)ss[row] * (SS_INV / 2048.0f) + RMS_EPS) * osc;
; template <class Epi, class Sched, bool ALIGN_EPI = false, bool SP2 = false, bool FP8 = false>
; __device__ __forceinline__ void gemm_phase(PG8_LAS unsigned char* lds, const Gemm g, const Sched& S, const Epi& E, const int tid) {
;     ...
;             PG8_WAIT_V(8); PG8_WAIT_L(0); PG8_BAR; PG8_MMA(1, 0, At, B0); PG8_MMA(1, 1, At, B1); PG8_BAR; PG8_SCHED;
;             PG8_LDB(B0, 1, 0); PG8_LDB(B1, 1, 1); PG8_SCHED; PG8_LDA(At, 1, 0); PG8_STAGE(PG8_SA(0, 1), a2 + hstepA, voffA);
;             PG8_WAIT_V(8); PG8_WAIT_L(0); PG8_BAR; PG8_MMA(0, 0, At, B0); PG8_MMA(0, 1, At, B1); PG8_BAR; PG8_SCHED;
;             PG8_LDA(At, 1, 1); PG8_STAGE(PG8_SB(1, 0), b3, voffB); PG8_STAGE(PG8_SB(1, 1), b3 + hstepB, voffB); PG8_STAGE(PG8_SA(1, 0), a3, voffA);
;             PG8_WAIT_V(8); PG8_WAIT_L(0); PG8_BAR; PG8_MMA(1, 0, At, B0); PG8_MMA(1, 1, At, B1); PG8_BAR; PG8_SCHED;
.Lskw_1_1:
	s_waitcnt lgkmcnt(0)
	s_barrier
	s_setprio 0
	s_waitcnt lgkmcnt(0)
	v_mfma_f32_16x16x128_f8f6f4 v[94:97], v[16:23], v[220:227], v[94:97]
	v_mfma_f32_16x16x128_f8f6f4 v[90:93], v[24:31], v[220:227], v[90:93]
	v_mfma_f32_16x16x128_f8f6f4 v[78:81], v[16:23], v[228:235], v[78:81]
	v_mfma_f32_16x16x128_f8f6f4 v[74:77], v[24:31], v[228:235], v[74:77]
	v_mfma_f32_16x16x128_f8f6f4 v[62:65], v[16:23], v[236:243], v[62:65]
	v_mfma_f32_16x16x128_f8f6f4 v[58:61], v[24:31], v[236:243], v[58:61]
	v_mfma_f32_16x16x128_f8f6f4 v[46:49], v[16:23], v[244:251], v[46:49]
	v_mfma_f32_16x16x128_f8f6f4 v[42:45], v[24:31], v[244:251], v[42:45]
	s_setprio 1
	s_setprio 0
	v_mfma_f32_16x16x128_f8f6f4 v[86:89], v[0:7], v[220:227], v[86:89]
	v_mfma_f32_16x16x128_f8f6f4 v[82:85], v[8:15], v[220:227], v[82:85]
	v_mfma_f32_16x16x128_f8f6f4 v[70:73], v[0:7], v[228:235], v[70:73]
	v_mfma_f32_16x16x128_f8f6f4 v[66:69], v[8:15], v[228:235], v[66:69]
	v_mfma_f32_16x16x128_f8f6f4 v[54:57], v[0:7], v[236:243], v[54:57]
	v_mfma_f32_16x16x128_f8f6f4 v[50:53], v[8:15], v[236:243], v[50:53]
	v_mfma_f32_16x16x128_f8f6f4 v[38:41], v[0:7], v[244:251], v[38:41]
	v_mfma_f32_16x16x128_f8f6f4 v[34:37], v[8:15], v[244:251], v[34:37]
	s_setprio 1
	s_barrier
	s_add_i32 s55, 0, 0x18000
	s_add_i32 s56, 0, 0x1c000
	v_add_u32_e32 v12, s55, v163
	v_add_u32_e32 v28, s56, v163
	ds_read_b128 v[0:3], v12
	ds_read_b128 v[4:7], v12 offset:1024
	ds_read_b128 v[8:11], v12 offset:2048
	ds_read_b128 v[12:15], v12 offset:3072
	ds_read_b128 v[16:19], v28
	ds_read_b128 v[20:23], v28 offset:1024
	ds_read_b128 v[24:27], v28 offset:2048
	ds_read_b128 v[28:31], v28 offset:3072
	s_add_u32 s36, s36, 0x40000
	s_addc_u32 s37, s37, 0
	s_mov_b32 m0, s47
	v_lshl_add_u64 v[164:165], s[36:37], 0, v[186:187]
	ds_read_b128 v[220:223], v200 offset:32768
	ds_read_b128 v[224:227], v200 offset:33792
	ds_read_b128 v[228:231], v200 offset:34816
	ds_read_b128 v[232:235], v200 offset:35840
	ds_read_b128 v[236:239], v200 offset:36864
	ds_read_b128 v[240:243], v200 offset:37888
	ds_read_b128 v[244:247], v200 offset:38912
	ds_read_b128 v[248:251], v200 offset:39936
	global_load_lds_dwordx4 v[164:165], off
	v_lshl_add_u64 v[164:165], s[36:37], 0, v[182:183]
	s_mov_b32 m0, s48
	s_nop 0
	global_load_lds_dwordx4 v[164:165], off
	s_waitcnt vmcnt(8)
	s_waitcnt lgkmcnt(0)
	s_barrier
	s_setprio 0
	s_waitcnt lgkmcnt(0)
	v_mfma_f32_16x16x128_f8f6f4 v[158:161], v[0:7], v[220:227], v[158:161]
	v_mfma_f32_16x16x128_f8f6f4 v[154:157], v[8:15], v[220:227], v[154:157]
	v_mfma_f32_16x16x128_f8f6f4 v[142:145], v[0:7], v[228:235], v[142:145]
	v_mfma_f32_16x16x128_f8f6f4 v[138:141], v[8:15], v[228:235], v[138:141]
	v_mfma_f32_16x16x128_f8f6f4 v[126:129], v[0:7], v[236:243], v[126:129]
	v_mfma_f32_16x16x128_f8f6f4 v[122:125], v[8:15], v[236:243], v[122:125]
	v_mfma_f32_16x16x128_f8f6f4 v[110:113], v[0:7], v[244:251], v[110:113]
	v_mfma_f32_16x16x128_f8f6f4 v[106:109], v[8:15], v[244:251], v[106:109]
	s_setprio 1
	s_setprio 0
	v_mfma_f32_16x16x128_f8f6f4 v[150:153], v[16:23], v[220:227], v[150:153]
	v_mfma_f32_16x16x128_f8f6f4 v[146:149], v[24:31], v[220:227], v[146:149]
	v_mfma_f32_16x16x128_f8f6f4 v[134:137], v[16:23], v[228:235], v[134:137]
	v_mfma_f32_16x16x128_f8f6f4 v[130:133], v[24:31], v[228:235], v[130:133]
	v_mfma_f32_16x16x128_f8f6f4 v[118:121], v[16:23], v[236:243], v[118:121]
	v_mfma_f32_16x16x128_f8f6f4 v[114:117], v[24:31], v[236:243], v[114:117]
	v_mfma_f32_16x16x128_f8f6f4 v[102:105], v[16:23], v[244:251], v[102:105]
	v_mfma_f32_16x16x128_f8f6f4 v[98:101], v[24:31], v[244:251], v[98:101]
	s_setprio 1
	s_barrier
	s_add_i32 s36, s55, s44
	v_lshl_add_u64 v[164:165], v[192:193], 0, s[38:39]
	s_mov_b32 m0, s36
	ds_read_b128 v[220:223], v200 offset:49152
	ds_read_b128 v[224:227], v200 offset:50176
	ds_read_b128 v[228:231], v200 offset:51200
	ds_read_b128 v[232:235], v200 offset:52224
	ds_read_b128 v[236:239], v200 offset:53248
	ds_read_b128 v[240:243], v200 offset:54272
	ds_read_b128 v[244:247], v200 offset:55296
	ds_read_b128 v[248:251], v200 offset:56320
	global_load_lds_dwordx4 v[164:165], off
	s_add_i32 m0, s36, 0x2000
	s_add_u32 s34, s34, 0x40080
	v_lshl_add_u64 v[164:165], v[194:195], 0, s[38:39]
	s_addc_u32 s35, s35, 0
	s_add_i32 s36, s56, s44
	global_load_lds_dwordx4 v[164:165], off
	v_lshl_add_u64 v[164:165], s[34:35], 0, v[184:185]
	s_mov_b32 m0, s36
	s_nop 0
	global_load_lds_dwordx4 v[164:165], off
	v_lshl_add_u64 v[164:165], s[34:35], 0, v[180:181]
	s_add_i32 m0, s36, 0x2000
	s_nop 0
	global_load_lds_dwordx4 v[164:165], off
	v_lshl_add_u64 v[164:165], v[196:197], 0, s[38:39]
	s_mov_b32 m0, s49
	s_nop 0
	global_load_lds_dwordx4 v[164:165], off
	v_lshl_add_u64 v[164:165], v[198:199], 0, s[38:39]
	s_mov_b32 m0, s50
	s_nop 0
	global_load_lds_dwordx4 v[164:165], off
	s_waitcnt vmcnt(8)
	s_waitcnt lgkmcnt(0)
	s_barrier
	s_setprio 0
	s_waitcnt lgkmcnt(0)
	v_mfma_f32_16x16x128_f8f6f4 v[94:97], v[0:7], v[220:227], v[94:97]
	v_mfma_f32_16x16x128_f8f6f4 v[90:93], v[8:15], v[220:227], v[90:93]
	v_mfma_f32_16x16x128_f8f6f4 v[78:81], v[0:7], v[228:235], v[78:81]
	v_mfma_f32_16x16x128_f8f6f4 v[74:77], v[8:15], v[228:235], v[74:77]
	v_mfma_f32_16x16x128_f8f6f4 v[62:65], v[0:7], v[236:243], v[62:65]
	v_mfma_f32_16x16x128_f8f6f4 v[58:61], v[8:15], v[236:243], v[58:61]
	v_mfma_f32_16x16x128_f8f6f4 v[46:49], v[0:7], v[244:251], v[46:49]
	v_mfma_f32_16x16x128_f8f6f4 v[42:45], v[8:15], v[244:251], v[42:45]
	s_setprio 1
	s_setprio 0
	v_mfma_f32_16x16x128_f8f6f4 v[86:89], v[16:23], v[220:227], v[86:89]
	v_mfma_f32_16x16x128_f8f6f4 v[82:85], v[24:31], v[220:227], v[82:85]
	v_mfma_f32_16x16x128_f8f6f4 v[70:73], v[16:23], v[228:235], v[70:73]
	v_mfma_f32_16x16x128_f8f6f4 v[66:69], v[24:31], v[228:235], v[66:69]
	v_mfma_f32_16x16x128_f8f6f4 v[54:57], v[16:23], v[236:243], v[54:57]
	v_mfma_f32_16x16x128_f8f6f4 v[50:53], v[24:31], v[236:243], v[50:53]
	v_mfma_f32_16x16x128_f8f6f4 v[38:41], v[16:23], v[244:251], v[38:41]
	v_mfma_f32_16x16x128_f8f6f4 v[34:37], v[24:31], v[244:251], v[34:37]
	s_setprio 1
	s_barrier
	s_add_i32 s54, s54, 2
	s_add_u32 s30, s30, 0x100
	s_addc_u32 s31, s31, 0
	s_add_u32 s52, s52, 0x100
	s_addc_u32 s53, s53, 0
	s_cmp_gt_u32 s54, 13
	s_cbranch_scc0 .LBB0_114
	s_setprio 0
	v_lshl_add_u32 v0, s20, 8, v33
	v_ashrrev_i32_e32 v1, 31, v0
	v_lshl_add_u64 v[2:3], v[0:1], 3, s[8:9]
	global_load_dwordx2 v[220:221], v[2:3], off
	global_load_dwordx2 v[222:223], v[2:3], off offset:128
	global_load_dwordx2 v[224:225], v[2:3], off offset:256
	global_load_dwordx2 v[226:227], v[2:3], off offset:384
	global_load_dwordx2 v[228:229], v[2:3], off offset:1024
	global_load_dwordx2 v[230:231], v[2:3], off offset:1152
	global_load_dwordx2 v[232:233], v[2:3], off offset:1280
	global_load_dwordx2 v[234:235], v[2:3], off offset:1408
	s_and_b64 vcc, exec, s[14:15]
	s_cbranch_vccz .LBB0_117
	s_barrier

; #define PG8_STAGE(bufoff, gbase, voff) do { _Pragma("unroll") for (int _i = 0; _i < 2; ++_i) \
;         __builtin_amdgcn_global_load_lds((const unsigned*)((const char*)(gbase) + (voff)[_i]), (PG8_LAS unsigned*)(lds + (bufoff) + ldsw + _i * 8192), 16, 0, 0); } while (0)
; #define PG8_WAIT_V(n) asm volatile("s_waitcnt vmcnt(" #n ")" ::: "memory")
; #define PG8_WAIT_L(n) asm volatile("s_waitcnt lgkmcnt(" #n ")" ::: "memory")
; #define PG8_BAR __builtin_amdgcn_s_barrier()
; #define PG8_SCHED __builtin_amdgcn_sched_barrier(0)
; template <class Epi, class Sched, bool ALIGN_EPI = false, bool SP2 = false, bool FP8 = false>
; __device__ __forceinline__ void gemm_phase(PG8_LAS unsigned char* lds, const Gemm g, const Sched& S, const Epi& E, const int tid) {
;     ...
;             PG8_WAIT_V(8); PG8_WAIT_L(0); PG8_BAR; PG8_MMA(0, 0, At, B0); PG8_MMA(0, 1, At, B1); PG8_BAR; PG8_SCHED;
;             PG8_LDA(At, 0, 1); PG8_STAGE(PG8_SB(0, 0), b2, voffB); PG8_STAGE(PG8_SB(0, 1), b2 + hstepB, voffB); PG8_STAGE(PG8_SA(0, 0), a2, voffA);
;             PG8_WAIT_V(8); PG8_WAIT_L(0); PG8_BAR; PG8_MMA(1, 0, At, B0); PG8_MMA(1, 1, At, B1); PG8_BAR; PG8_SCHED;
.Lskw_2_0:
	s_waitcnt lgkmcnt(0)
	s_barrier
	s_setprio 0
	s_waitcnt lgkmcnt(0)
	v_mfma_f32_16x16x32_bf16 v[126:129], v[130:133], v[192:195], v[126:129]
	v_mfma_f32_16x16x32_bf16 v[122:125], v[138:141], v[192:195], v[122:125]
	v_mfma_f32_16x16x32_bf16 v[118:121], v[130:133], v[224:227], v[118:121]
	v_mfma_f32_16x16x32_bf16 v[114:117], v[138:141], v[224:227], v[114:117]
	v_mfma_f32_16x16x32_bf16 v[110:113], v[130:133], v[232:235], v[110:113]
	v_mfma_f32_16x16x32_bf16 v[106:109], v[138:141], v[232:235], v[106:109]
	v_mfma_f32_16x16x32_bf16 v[102:105], v[130:133], v[240:243], v[102:105]
	v_mfma_f32_16x16x32_bf16 v[98:101], v[138:141], v[240:243], v[98:101]
	v_mfma_f32_16x16x32_bf16 v[126:129], v[134:137], v[220:223], v[126:129]
	v_mfma_f32_16x16x32_bf16 v[122:125], v[142:145], v[220:223], v[122:125]
	v_mfma_f32_16x16x32_bf16 v[118:121], v[134:137], v[228:231], v[118:121]
	v_mfma_f32_16x16x32_bf16 v[114:117], v[142:145], v[228:231], v[114:117]
	v_mfma_f32_16x16x32_bf16 v[110:113], v[134:137], v[236:239], v[110:113]
	v_mfma_f32_16x16x32_bf16 v[106:109], v[142:145], v[236:239], v[106:109]
	v_mfma_f32_16x16x32_bf16 v[102:105], v[134:137], v[244:247], v[102:105]
	v_mfma_f32_16x16x32_bf16 v[98:101], v[142:145], v[244:247], v[98:101]
	s_setprio 1
	s_setprio 0
	v_mfma_f32_16x16x32_bf16 v[94:97], v[146:149], v[192:195], v[94:97]
	v_mfma_f32_16x16x32_bf16 v[90:93], v[154:157], v[192:195], v[90:93]
	v_mfma_f32_16x16x32_bf16 v[86:89], v[146:149], v[224:227], v[86:89]
	v_mfma_f32_16x16x32_bf16 v[82:85], v[154:157], v[224:227], v[82:85]
	v_mfma_f32_16x16x32_bf16 v[78:81], v[146:149], v[232:235], v[78:81]
	v_mfma_f32_16x16x32_bf16 v[74:77], v[154:157], v[232:235], v[74:77]
	v_mfma_f32_16x16x32_bf16 v[70:73], v[146:149], v[240:243], v[70:73]
	v_mfma_f32_16x16x32_bf16 v[66:69], v[154:157], v[240:243], v[66:69]
	v_mfma_f32_16x16x32_bf16 v[94:97], v[150:153], v[220:223], v[94:97]
	v_mfma_f32_16x16x32_bf16 v[90:93], v[158:161], v[220:223], v[90:93]
	v_mfma_f32_16x16x32_bf16 v[86:89], v[150:153], v[228:231], v[86:89]
	v_mfma_f32_16x16x32_bf16 v[82:85], v[158:161], v[228:231], v[82:85]
	v_mfma_f32_16x16x32_bf16 v[78:81], v[150:153], v[236:239], v[78:81]
	v_mfma_f32_16x16x32_bf16 v[74:77], v[158:161], v[236:239], v[74:77]
	v_mfma_f32_16x16x32_bf16 v[70:73], v[150:153], v[244:247], v[70:73]
	v_mfma_f32_16x16x32_bf16 v[66:69], v[158:161], v[244:247], v[66:69]
	s_setprio 1
	s_barrier
	s_add_i32 s8, s61, s45
	v_lshl_add_u64 v[164:165], s[34:35], 0, v[184:185]
	s_mov_b32 m0, s8
	ds_read_b128 v[192:195], v198 offset:16384
	ds_read_b128 v[220:223], v198 offset:17408
	ds_read_b128 v[224:227], v198 offset:18432
	ds_read_b128 v[228:231], v198 offset:19456
	ds_read_b128 v[232:235], v198 offset:20480
	ds_read_b128 v[236:239], v198 offset:21504
	ds_read_b128 v[240:243], v198 offset:22528
	ds_read_b128 v[244:247], v198 offset:23552
	global_load_lds_dwordx4 v[164:165], off
	s_add_i32 m0, s8, 0x2000
	s_add_u32 s8, s34, 0x40000
	v_lshl_add_u64 v[166:167], s[34:35], 0, v[180:181]
	s_addc_u32 s9, s35, 0
	s_add_i32 s61, s62, s45
	global_load_lds_dwordx4 v[166:167], off
	v_lshl_add_u64 v[196:197], s[8:9], 0, v[184:185]
	s_mov_b32 m0, s61
	v_lshl_add_u64 v[200:201], s[36:37], 0, v[182:183]
	global_load_lds_dwordx4 v[196:197], off
	v_lshl_add_u64 v[196:197], s[8:9], 0, v[180:181]
	s_add_i32 m0, s61, 0x2000
	s_nop 0
	global_load_lds_dwordx4 v[196:197], off
	v_lshl_add_u64 v[196:197], s[36:37], 0, v[186:187]
	s_mov_b32 m0, s46
	s_nop 0
	global_load_lds_dwordx4 v[196:197], off
	s_mov_b32 m0, s47
	s_nop 0
	global_load_lds_dwordx4 v[200:201], off
	s_cmp_eq_i32 s60, 2
	s_cbranch_scc1 .Lskw_2_1
	s_waitcnt vmcnt(8)
.Lskw_2_1:
	s_waitcnt lgkmcnt(0)
	s_barrier
	s_setprio 0
	s_waitcnt lgkmcnt(0)
	v_mfma_f32_16x16x32_bf16 v[62:65], v[130:133], v[192:195], v[62:65]
	v_mfma_f32_16x16x32_bf16 v[58:61], v[138:141], v[192:195], v[58:61]
	v_mfma_f32_16x16x32_bf16 v[54:57], v[130:133], v[224:227], v[54:57]
	v_mfma_f32_16x16x32_bf16 v[50:53], v[138:141], v[224:227], v[50:53]
	v_mfma_f32_16x16x32_bf16 v[46:49], v[130:133], v[232:235], v[46:49]
	v_mfma_f32_16x16x32_bf16 v[42:45], v[138:141], v[232:235], v[42:45]
	v_mfma_f32_16x16x32_bf16 v[38:41], v[130:133], v[240:243], v[38:41]
	v_mfma_f32_16x16x32_bf16 v[34:37], v[138:141], v[240:243], v[34:37]
	v_mfma_f32_16x16x32_bf16 v[62:65], v[134:137], v[220:223], v[62:65]
	v_mfma_f32_16x16x32_bf16 v[58:61], v[142:145], v[220:223], v[58:61]
	v_mfma_f32_16x16x32_bf16 v[54:57], v[134:137], v[228:231], v[54:57]
	v_mfma_f32_16x16x32_bf16 v[50:53], v[142:145], v[228:231], v[50:53]
	v_mfma_f32_16x16x32_bf16 v[46:49], v[134:137], v[236:239], v[46:49]
	v_mfma_f32_16x16x32_bf16 v[42:45], v[142:145], v[236:239], v[42:45]
	v_mfma_f32_16x16x32_bf16 v[38:41], v[134:137], v[244:247], v[38:41]
	v_mfma_f32_16x16x32_bf16 v[34:37], v[142:145], v[244:247], v[34:37]
	s_setprio 1
	s_setprio 0
	v_mfma_f32_16x16x32_bf16 v[28:31], v[146:149], v[192:195], v[28:31]
	v_mfma_f32_16x16x32_bf16 v[24:27], v[154:157], v[192:195], v[24:27]
	v_mfma_f32_16x16x32_bf16 v[20:23], v[146:149], v[224:227], v[20:23]
	v_mfma_f32_16x16x32_bf16 v[16:19], v[154:157], v[224:227], v[16:19]
	v_mfma_f32_16x16x32_bf16 v[12:15], v[146:149], v[232:235], v[12:15]
	v_mfma_f32_16x16x32_bf16 v[8:11], v[154:157], v[232:235], v[8:11]
	v_mfma_f32_16x16x32_bf16 v[4:7], v[146:149], v[240:243], v[4:7]
	v_mfma_f32_16x16x32_bf16 v[0:3], v[154:157], v[240:243], v[0:3]
	v_mfma_f32_16x16x32_bf16 v[28:31], v[150:153], v[220:223], v[28:31]
	v_mfma_f32_16x16x32_bf16 v[24:27], v[158:161], v[220:223], v[24:27]
	v_mfma_f32_16x16x32_bf16 v[20:23], v[150:153], v[228:231], v[20:23]
	v_mfma_f32_16x16x32_bf16 v[16:19], v[158:161], v[228:231], v[16:19]
	v_mfma_f32_16x16x32_bf16 v[12:15], v[150:153], v[236:239], v[12:15]
	v_mfma_f32_16x16x32_bf16 v[8:11], v[158:161], v[236:239], v[8:11]
	v_mfma_f32_16x16x32_bf16 v[4:7], v[150:153], v[244:247], v[4:7]
	v_mfma_f32_16x16x32_bf16 v[0:3], v[158:161], v[244:247], v[0:3]
	s_setprio 1
	s_barrier
; #define PG8_STAGE(bufoff, gbase, voff) do { _Pragma("unroll") for (int _i = 0; _i < 2; ++_i) \
;         __builtin_amdgcn_global_load_lds((const unsigned*)((const char*)(gbase) + (voff)[_i]), (PG8_LAS unsigned*)(lds + (bufoff) + ldsw + _i * 8192), 16, 0, 0); } while (0)
; #define PG8_WAIT_V(n) asm volatile("s_waitcnt vmcnt(" #n ")" ::: "memory")
; #define PG8_WAIT_L(n) asm volatile("s_waitcnt lgkmcnt(" #n ")" ::: "memory")
; #define PG8_BAR __builtin_amdgcn_s_barrier()
; #define PG8_SCHED __builtin_amdgcn_sched_barrier(0)
; template <class Epi, class Sched, bool ALIGN_EPI = false, bool SP2 = false, bool FP8 = false>
; __device__ __forceinline__ void gemm_phase(PG8_LAS unsigned char* lds, const Gemm g, const Sched& S, const Epi& E, const int tid) {
;     ...
;             PG8_LDB(B0, 1, 0); PG8_LDB(B1, 1, 1); PG8_SCHED; PG8_LDA(At, 1, 0); PG8_STAGE(PG8_SA(0, 1), a2 + hstepA, voffA);
;             PG8_WAIT_V(8); PG8_WAIT_L(0); PG8_BAR; PG8_MMA(0, 0, At, B0); PG8_MMA(0, 1, At, B1); PG8_BAR; PG8_SCHED;
	s_add_i32 s61, 0, 0x18000
	s_add_i32 s62, 0, 0x1c000
	v_add_u32_e32 v142, s61, v163
	v_add_u32_e32 v158, s62, v163
	ds_read_b128 v[130:133], v142
	ds_read_b128 v[134:137], v142 offset:1024
	ds_read_b128 v[138:141], v142 offset:2048
	ds_read_b128 v[142:145], v142 offset:3072
	ds_read_b128 v[146:149], v158
	ds_read_b128 v[150:153], v158 offset:1024
	ds_read_b128 v[154:157], v158 offset:2048
	ds_read_b128 v[158:161], v158 offset:3072
	s_add_u32 s8, s36, 0x3c0000
	s_addc_u32 s9, s37, 0
	s_mov_b32 m0, s48
	v_lshl_add_u64 v[248:249], s[8:9], 0, v[186:187]
	ds_read_b128 v[192:195], v198 offset:32768
	ds_read_b128 v[220:223], v198 offset:33792
	ds_read_b128 v[224:227], v198 offset:34816
	ds_read_b128 v[228:231], v198 offset:35840
	ds_read_b128 v[232:235], v198 offset:36864
	ds_read_b128 v[236:239], v198 offset:37888
	ds_read_b128 v[240:243], v198 offset:38912
	ds_read_b128 v[244:247], v198 offset:39936
	global_load_lds_dwordx4 v[248:249], off
	v_lshl_add_u64 v[248:249], s[8:9], 0, v[182:183]
	s_mov_b32 m0, s49
	s_nop 0
	global_load_lds_dwordx4 v[248:249], off
	s_waitcnt vmcnt(8)
	s_waitcnt lgkmcnt(0)
	s_barrier
	s_setprio 0
	s_waitcnt lgkmcnt(0)
	v_mfma_f32_16x16x32_bf16 v[126:129], v[130:133], v[192:195], v[126:129]
	v_mfma_f32_16x16x32_bf16 v[122:125], v[138:141], v[192:195], v[122:125]
	v_mfma_f32_16x16x32_bf16 v[118:121], v[130:133], v[224:227], v[118:121]
	v_mfma_f32_16x16x32_bf16 v[114:117], v[138:141], v[224:227], v[114:117]
	v_mfma_f32_16x16x32_bf16 v[110:113], v[130:133], v[232:235], v[110:113]
	v_mfma_f32_16x16x32_bf16 v[106:109], v[138:141], v[232:235], v[106:109]
	v_mfma_f32_16x16x32_bf16 v[102:105], v[130:133], v[240:243], v[102:105]
	v_mfma_f32_16x16x32_bf16 v[98:101], v[138:141], v[240:243], v[98:101]
	v_mfma_f32_16x16x32_bf16 v[126:129], v[134:137], v[220:223], v[126:129]
	v_mfma_f32_16x16x32_bf16 v[122:125], v[142:145], v[220:223], v[122:125]
	v_mfma_f32_16x16x32_bf16 v[118:121], v[134:137], v[228:231], v[118:121]
	v_mfma_f32_16x16x32_bf16 v[114:117], v[142:145], v[228:231], v[114:117]
	v_mfma_f32_16x16x32_bf16 v[110:113], v[134:137], v[236:239], v[110:113]
	v_mfma_f32_16x16x32_bf16 v[106:109], v[142:145], v[236:239], v[106:109]
	v_mfma_f32_16x16x32_bf16 v[102:105], v[134:137], v[244:247], v[102:105]
	v_mfma_f32_16x16x32_bf16 v[98:101], v[142:145], v[244:247], v[98:101]
	s_setprio 1
	s_setprio 0
	v_mfma_f32_16x16x32_bf16 v[94:97], v[146:149], v[192:195], v[94:97]
	v_mfma_f32_16x16x32_bf16 v[90:93], v[154:157], v[192:195], v[90:93]
	v_mfma_f32_16x16x32_bf16 v[86:89], v[146:149], v[224:227], v[86:89]
	v_mfma_f32_16x16x32_bf16 v[82:85], v[154:157], v[224:227], v[82:85]
	v_mfma_f32_16x16x32_bf16 v[78:81], v[146:149], v[232:235], v[78:81]
	v_mfma_f32_16x16x32_bf16 v[74:77], v[154:157], v[232:235], v[74:77]
	v_mfma_f32_16x16x32_bf16 v[70:73], v[146:149], v[240:243], v[70:73]
	v_mfma_f32_16x16x32_bf16 v[66:69], v[154:157], v[240:243], v[66:69]
	v_mfma_f32_16x16x32_bf16 v[94:97], v[150:153], v[220:223], v[94:97]
	v_mfma_f32_16x16x32_bf16 v[90:93], v[158:161], v[220:223], v[90:93]
	v_mfma_f32_16x16x32_bf16 v[86:89], v[150:153], v[228:231], v[86:89]
	v_mfma_f32_16x16x32_bf16 v[82:85], v[158:161], v[228:231], v[82:85]
	v_mfma_f32_16x16x32_bf16 v[78:81], v[150:153], v[236:239], v[78:81]
	v_mfma_f32_16x16x32_bf16 v[74:77], v[158:161], v[236:239], v[74:77]
	v_mfma_f32_16x16x32_bf16 v[70:73], v[150:153], v[244:247], v[70:73]
	v_mfma_f32_16x16x32_bf16 v[66:69], v[158:161], v[244:247], v[66:69]
	s_setprio 1
	s_barrier
; #define PG8_STAGE(bufoff, gbase, voff) do { _Pragma("unroll") for (int _i = 0; _i < 2; ++_i) \
;         __builtin_amdgcn_global_load_lds((const unsigned*)((const char*)(gbase) + (voff)[_i]), (PG8_LAS unsigned*)(lds + (bufoff) + ldsw + _i * 8192), 16, 0, 0); } while (0)
; #define PG8_WAIT_V(n) asm volatile("s_waitcnt vmcnt(" #n ")" ::: "memory")
; #define PG8_WAIT_L(n) asm volatile("s_waitcnt lgkmcnt(" #n ")" ::: "memory")
; #define PG8_BAR __builtin_amdgcn_s_barrier()
; #define PG8_SCHED __builtin_amdgcn_sched_barrier(0)
; template <class Epi, class Sched, bool ALIGN_EPI = false, bool SP2 = false, bool FP8 = false>
; __device__ __forceinline__ void gemm_phase(PG8_LAS unsigned char* lds, const Gemm g, const Sched& S, const Epi& E, const int tid) {
;     ...
;             PG8_LDA(At, 1, 1); PG8_STAGE(PG8_SB(1, 0), b3, voffB); PG8_STAGE(PG8_SB(1, 1), b3 + hstepB, voffB); PG8_STAGE(PG8_SA(1, 0), a3, voffA);
;             PG8_WAIT_V(8); PG8_WAIT_L(0); PG8_BAR; PG8_MMA(1, 0, At, B0); PG8_MMA(1, 1, At, B1); PG8_BAR; PG8_SCHED;
	s_add_i32 s8, s61, s45
	v_lshl_add_u64 v[164:165], v[164:165], 0, s[38:39]
	s_mov_b32 m0, s8
	ds_read_b128 v[192:195], v198 offset:49152
	ds_read_b128 v[220:223], v198 offset:50176
	ds_read_b128 v[224:227], v198 offset:51200
	ds_read_b128 v[228:231], v198 offset:52224
	ds_read_b128 v[232:235], v198 offset:53248
	ds_read_b128 v[236:239], v198 offset:54272
	ds_read_b128 v[240:243], v198 offset:55296
	ds_read_b128 v[244:247], v198 offset:56320
	global_load_lds_dwordx4 v[164:165], off
	s_add_i32 m0, s8, 0x2000
	s_add_u32 s8, s34, 0x40080
	v_lshl_add_u64 v[164:165], v[166:167], 0, s[38:39]
	s_addc_u32 s9, s35, 0
	s_add_i32 s34, s62, s45
	global_load_lds_dwordx4 v[164:165], off
	v_lshl_add_u64 v[164:165], s[8:9], 0, v[184:185]
	s_mov_b32 m0, s34
	s_nop 0
	global_load_lds_dwordx4 v[164:165], off
	v_lshl_add_u64 v[164:165], s[8:9], 0, v[180:181]
	s_add_i32 m0, s34, 0x2000
	s_nop 0
	global_load_lds_dwordx4 v[164:165], off
	v_lshl_add_u64 v[164:165], v[196:197], 0, s[38:39]
	s_mov_b32 m0, s52
	s_nop 0
	global_load_lds_dwordx4 v[164:165], off
	v_lshl_add_u64 v[164:165], v[200:201], 0, s[38:39]
	s_mov_b32 m0, s53
	s_nop 0
	global_load_lds_dwordx4 v[164:165], off
	s_waitcnt vmcnt(8)
	s_waitcnt lgkmcnt(0)
	s_barrier
	s_setprio 0
	s_waitcnt lgkmcnt(0)
	v_mfma_f32_16x16x32_bf16 v[62:65], v[130:133], v[192:195], v[62:65]
	v_mfma_f32_16x16x32_bf16 v[58:61], v[138:141], v[192:195], v[58:61]
	v_mfma_f32_16x16x32_bf16 v[54:57], v[130:133], v[224:227], v[54:57]
	v_mfma_f32_16x16x32_bf16 v[50:53], v[138:141], v[224:227], v[50:53]
	v_mfma_f32_16x16x32_bf16 v[46:49], v[130:133], v[232:235], v[46:49]
	v_mfma_f32_16x16x32_bf16 v[42:45], v[138:141], v[232:235], v[42:45]
	v_mfma_f32_16x16x32_bf16 v[38:41], v[130:133], v[240:243], v[38:41]
	v_mfma_f32_16x16x32_bf16 v[34:37], v[138:141], v[240:243], v[34:37]
	v_mfma_f32_16x16x32_bf16 v[62:65], v[134:137], v[220:223], v[62:65]
	v_mfma_f32_16x16x32_bf16 v[58:61], v[142:145], v[220:223], v[58:61]
	v_mfma_f32_16x16x32_bf16 v[54:57], v[134:137], v[228:231], v[54:57]
	v_mfma_f32_16x16x32_bf16 v[50:53], v[142:145], v[228:231], v[50:53]
	v_mfma_f32_16x16x32_bf16 v[46:49], v[134:137], v[236:239], v[46:49]
	v_mfma_f32_16x16x32_bf16 v[42:45], v[142:145], v[236:239], v[42:45]
	v_mfma_f32_16x16x32_bf16 v[38:41], v[134:137], v[244:247], v[38:41]
	v_mfma_f32_16x16x32_bf16 v[34:37], v[142:145], v[244:247], v[34:37]
	s_setprio 1
	s_setprio 0
	v_mfma_f32_16x16x32_bf16 v[28:31], v[146:149], v[192:195], v[28:31]
	v_mfma_f32_16x16x32_bf16 v[24:27], v[154:157], v[192:195], v[24:27]
	v_mfma_f32_16x16x32_bf16 v[20:23], v[146:149], v[224:227], v[20:23]
	v_mfma_f32_16x16x32_bf16 v[16:19], v[154:157], v[224:227], v[16:19]
	v_mfma_f32_16x16x32_bf16 v[12:15], v[146:149], v[232:235], v[12:15]
	v_mfma_f32_16x16x32_bf16 v[8:11], v[154:157], v[232:235], v[8:11]
	v_mfma_f32_16x16x32_bf16 v[4:7], v[146:149], v[240:243], v[4:7]
	v_mfma_f32_16x16x32_bf16 v[0:3], v[154:157], v[240:243], v[0:3]
	v_mfma_f32_16x16x32_bf16 v[28:31], v[150:153], v[220:223], v[28:31]
	v_mfma_f32_16x16x32_bf16 v[24:27], v[158:161], v[220:223], v[24:27]
	v_mfma_f32_16x16x32_bf16 v[20:23], v[150:153], v[228:231], v[20:23]
	v_mfma_f32_16x16x32_bf16 v[16:19], v[158:161], v[228:231], v[16:19]
	v_mfma_f32_16x16x32_bf16 v[12:15], v[150:153], v[236:239], v[12:15]
	v_mfma_f32_16x16x32_bf16 v[8:11], v[158:161], v[236:239], v[8:11]
	v_mfma_f32_16x16x32_bf16 v[4:7], v[150:153], v[244:247], v[4:7]
	v_mfma_f32_16x16x32_bf16 v[0:3], v[158:161], v[244:247], v[0:3]
	s_setprio 1
	s_barrier
	s_add_u32 s58, s58, 0x100
	s_addc_u32 s59, s59, 0
	s_cmp_ge_u32 s60, s27
	s_mov_b64 s[8:9], s[6:7]
	s_mov_b32 s36, s60
	s_cbranch_scc0 .LBB0_457
	s_setprio 0
	s_and_b64 vcc, exec, s[24:25]
	s_cbranch_vccz .LBB0_460
	s_barrier

; #define PG8_STAGE(bufoff, gbase, voff) do { _Pragma("unroll") for (int _i = 0; _i < 2; ++_i) \
;         __builtin_amdgcn_global_load_lds((const unsigned*)((const char*)(gbase) + (voff)[_i]), (PG8_LAS unsigned*)(lds + (bufoff) + ldsw + _i * 8192), 16, 0, 0); } while (0)
; #define PG8_WAIT_V(n) asm volatile("s_waitcnt vmcnt(" #n ")" ::: "memory")
; #define PG8_WAIT_L(n) asm volatile("s_waitcnt lgkmcnt(" #n ")" ::: "memory")
; #define PG8_BAR __builtin_amdgcn_s_barrier()
; #define PG8_SCHED __builtin_amdgcn_sched_barrier(0)
; template <class Epi, class Sched, bool ALIGN_EPI = false, bool SP2 = false, bool FP8 = false>
; __device__ __forceinline__ void gemm_phase(PG8_LAS unsigned char* lds, const Gemm g, const Sched& S, const Epi& E, const int tid) {
;     ...
;             PG8_WAIT_V(8); PG8_WAIT_L(0); PG8_BAR; PG8_MMA(0, 0, At, B0); PG8_MMA(0, 1, At, B1); PG8_BAR; PG8_SCHED;
;             PG8_LDA(At, 0, 1); PG8_STAGE(PG8_SB(0, 0), b2, voffB); PG8_STAGE(PG8_SB(0, 1), b2 + hstepB, voffB); PG8_STAGE(PG8_SA(0, 0), a2, voffA);
;             PG8_WAIT_V(8); PG8_WAIT_L(0); PG8_BAR; PG8_MMA(1, 0, At, B0); PG8_MMA(1, 1, At, B1); PG8_BAR; PG8_SCHED;
.Lskw_3_0:
	s_waitcnt lgkmcnt(0)
	s_barrier
	s_setprio 0
	s_waitcnt lgkmcnt(0)
	v_mfma_f32_16x16x32_bf16 v[126:129], v[130:133], v[192:195], v[126:129]
	v_mfma_f32_16x16x32_bf16 v[122:125], v[138:141], v[192:195], v[122:125]
	v_mfma_f32_16x16x32_bf16 v[110:113], v[130:133], v[222:225], v[110:113]
	v_mfma_f32_16x16x32_bf16 v[106:109], v[138:141], v[222:225], v[106:109]
	v_mfma_f32_16x16x32_bf16 v[94:97], v[130:133], v[230:233], v[94:97]
	v_mfma_f32_16x16x32_bf16 v[90:93], v[138:141], v[230:233], v[90:93]
	v_mfma_f32_16x16x32_bf16 v[78:81], v[130:133], v[238:241], v[78:81]
	v_mfma_f32_16x16x32_bf16 v[74:77], v[138:141], v[238:241], v[74:77]
	v_mfma_f32_16x16x32_bf16 v[126:129], v[134:137], v[196:199], v[126:129]
	v_mfma_f32_16x16x32_bf16 v[122:125], v[142:145], v[196:199], v[122:125]
	v_mfma_f32_16x16x32_bf16 v[110:113], v[134:137], v[226:229], v[110:113]
	v_mfma_f32_16x16x32_bf16 v[106:109], v[142:145], v[226:229], v[106:109]
	v_mfma_f32_16x16x32_bf16 v[94:97], v[134:137], v[234:237], v[94:97]
	v_mfma_f32_16x16x32_bf16 v[90:93], v[142:145], v[234:237], v[90:93]
	v_mfma_f32_16x16x32_bf16 v[78:81], v[134:137], v[242:245], v[78:81]
	v_mfma_f32_16x16x32_bf16 v[74:77], v[142:145], v[242:245], v[74:77]
	s_setprio 1
	s_setprio 0
	v_mfma_f32_16x16x32_bf16 v[118:121], v[146:149], v[192:195], v[118:121]
	v_mfma_f32_16x16x32_bf16 v[114:117], v[154:157], v[192:195], v[114:117]
	v_mfma_f32_16x16x32_bf16 v[102:105], v[146:149], v[222:225], v[102:105]
	v_mfma_f32_16x16x32_bf16 v[98:101], v[154:157], v[222:225], v[98:101]
	v_mfma_f32_16x16x32_bf16 v[86:89], v[146:149], v[230:233], v[86:89]
	v_mfma_f32_16x16x32_bf16 v[82:85], v[154:157], v[230:233], v[82:85]
	v_mfma_f32_16x16x32_bf16 v[70:73], v[146:149], v[238:241], v[70:73]
	v_mfma_f32_16x16x32_bf16 v[66:69], v[154:157], v[238:241], v[66:69]
	v_mfma_f32_16x16x32_bf16 v[118:121], v[150:153], v[196:199], v[118:121]
	v_mfma_f32_16x16x32_bf16 v[114:117], v[158:161], v[196:199], v[114:117]
	v_mfma_f32_16x16x32_bf16 v[102:105], v[150:153], v[226:229], v[102:105]
	v_mfma_f32_16x16x32_bf16 v[98:101], v[158:161], v[226:229], v[98:101]
	v_mfma_f32_16x16x32_bf16 v[86:89], v[150:153], v[234:237], v[86:89]
	v_mfma_f32_16x16x32_bf16 v[82:85], v[158:161], v[234:237], v[82:85]
	v_mfma_f32_16x16x32_bf16 v[70:73], v[150:153], v[242:245], v[70:73]
	v_mfma_f32_16x16x32_bf16 v[66:69], v[158:161], v[242:245], v[66:69]
	s_setprio 1
	s_barrier
	s_add_i32 s63, s63, s52
	v_lshl_add_u64 v[164:165], s[44:45], 0, v[184:185]
	s_mov_b32 m0, s63
	ds_read_b128 v[192:195], v220 offset:16384
	ds_read_b128 v[196:199], v220 offset:17408
	ds_read_b128 v[222:225], v220 offset:18432
	ds_read_b128 v[226:229], v220 offset:19456
	ds_read_b128 v[230:233], v220 offset:20480
	ds_read_b128 v[234:237], v220 offset:21504
	ds_read_b128 v[238:241], v220 offset:22528
	ds_read_b128 v[242:245], v220 offset:23552
	global_load_lds_dwordx4 v[164:165], off
	s_add_i32 m0, s63, 0x2000
	s_add_u32 s64, s44, 0x80000
	v_lshl_add_u64 v[166:167], s[44:45], 0, v[180:181]
	s_addc_u32 s65, s45, 0
	s_add_i32 s63, s66, s52
	global_load_lds_dwordx4 v[166:167], off
	v_lshl_add_u64 v[200:201], s[64:65], 0, v[184:185]
	s_mov_b32 m0, s63
	v_lshl_add_u64 v[246:247], s[46:47], 0, v[182:183]
	global_load_lds_dwordx4 v[200:201], off
	v_lshl_add_u64 v[200:201], s[64:65], 0, v[180:181]
	s_add_i32 m0, s63, 0x2000
	s_nop 0
	global_load_lds_dwordx4 v[200:201], off
	v_lshl_add_u64 v[200:201], s[46:47], 0, v[186:187]
	s_mov_b32 m0, s53
	s_nop 0
	global_load_lds_dwordx4 v[200:201], off
	s_mov_b32 m0, s54
	s_nop 0
	global_load_lds_dwordx4 v[246:247], off
	s_cmp_eq_i32 s62, -2
	s_cbranch_scc1 .Lskw_3_1
	s_waitcnt vmcnt(8)
.Lskw_3_1:
	s_waitcnt lgkmcnt(0)
	s_barrier
	s_setprio 0
	s_waitcnt lgkmcnt(0)
	v_mfma_f32_16x16x32_bf16 v[62:65], v[130:133], v[192:195], v[62:65]
	v_mfma_f32_16x16x32_bf16 v[58:61], v[138:141], v[192:195], v[58:61]
	v_mfma_f32_16x16x32_bf16 v[46:49], v[130:133], v[222:225], v[46:49]
	v_mfma_f32_16x16x32_bf16 v[42:45], v[138:141], v[222:225], v[42:45]
	v_mfma_f32_16x16x32_bf16 v[28:31], v[130:133], v[230:233], v[28:31]
	v_mfma_f32_16x16x32_bf16 v[24:27], v[138:141], v[230:233], v[24:27]
	v_mfma_f32_16x16x32_bf16 v[12:15], v[130:133], v[238:241], v[12:15]
	v_mfma_f32_16x16x32_bf16 v[8:11], v[138:141], v[238:241], v[8:11]
	v_mfma_f32_16x16x32_bf16 v[62:65], v[134:137], v[196:199], v[62:65]
	v_mfma_f32_16x16x32_bf16 v[58:61], v[142:145], v[196:199], v[58:61]
	v_mfma_f32_16x16x32_bf16 v[46:49], v[134:137], v[226:229], v[46:49]
	v_mfma_f32_16x16x32_bf16 v[42:45], v[142:145], v[226:229], v[42:45]
	v_mfma_f32_16x16x32_bf16 v[28:31], v[134:137], v[234:237], v[28:31]
	v_mfma_f32_16x16x32_bf16 v[24:27], v[142:145], v[234:237], v[24:27]
	v_mfma_f32_16x16x32_bf16 v[12:15], v[134:137], v[242:245], v[12:15]
	v_mfma_f32_16x16x32_bf16 v[8:11], v[142:145], v[242:245], v[8:11]
	s_setprio 1
	s_setprio 0
	v_mfma_f32_16x16x32_bf16 v[54:57], v[146:149], v[192:195], v[54:57]
	v_mfma_f32_16x16x32_bf16 v[50:53], v[154:157], v[192:195], v[50:53]
	v_mfma_f32_16x16x32_bf16 v[38:41], v[146:149], v[222:225], v[38:41]
	v_mfma_f32_16x16x32_bf16 v[34:37], v[154:157], v[222:225], v[34:37]
	v_mfma_f32_16x16x32_bf16 v[20:23], v[146:149], v[230:233], v[20:23]
	v_mfma_f32_16x16x32_bf16 v[16:19], v[154:157], v[230:233], v[16:19]
	v_mfma_f32_16x16x32_bf16 v[4:7], v[146:149], v[238:241], v[4:7]
	v_mfma_f32_16x16x32_bf16 v[0:3], v[154:157], v[238:241], v[0:3]
	v_mfma_f32_16x16x32_bf16 v[54:57], v[150:153], v[196:199], v[54:57]
	v_mfma_f32_16x16x32_bf16 v[50:53], v[158:161], v[196:199], v[50:53]
	v_mfma_f32_16x16x32_bf16 v[38:41], v[150:153], v[226:229], v[38:41]
	v_mfma_f32_16x16x32_bf16 v[34:37], v[158:161], v[226:229], v[34:37]
	v_mfma_f32_16x16x32_bf16 v[20:23], v[150:153], v[234:237], v[20:23]
	v_mfma_f32_16x16x32_bf16 v[16:19], v[158:161], v[234:237], v[16:19]
	v_mfma_f32_16x16x32_bf16 v[4:7], v[150:153], v[242:245], v[4:7]
	v_mfma_f32_16x16x32_bf16 v[0:3], v[158:161], v[242:245], v[0:3]
	s_setprio 1
	s_barrier
; #define PG8_STAGE(bufoff, gbase, voff) do { _Pragma("unroll") for (int _i = 0; _i < 2; ++_i) \
;         __builtin_amdgcn_global_load_lds((const unsigned*)((const char*)(gbase) + (voff)[_i]), (PG8_LAS unsigned*)(lds + (bufoff) + ldsw + _i * 8192), 16, 0, 0); } while (0)
; #define PG8_WAIT_V(n) asm volatile("s_waitcnt vmcnt(" #n ")" ::: "memory")
; #define PG8_WAIT_L(n) asm volatile("s_waitcnt lgkmcnt(" #n ")" ::: "memory")
; #define PG8_BAR __builtin_amdgcn_s_barrier()
; #define PG8_SCHED __builtin_amdgcn_sched_barrier(0)
; template <class Epi, class Sched, bool ALIGN_EPI = false, bool SP2 = false, bool FP8 = false>
; __device__ __forceinline__ void gemm_phase(PG8_LAS unsigned char* lds, const Gemm g, const Sched& S, const Epi& E, const int tid) {
;     ...
;             PG8_LDB(B0, 1, 0); PG8_LDB(B1, 1, 1); PG8_SCHED; PG8_LDA(At, 1, 0); PG8_STAGE(PG8_SA(0, 1), a2 + hstepA, voffA);
;             PG8_WAIT_V(8); PG8_WAIT_L(0); PG8_BAR; PG8_MMA(0, 0, At, B0); PG8_MMA(0, 1, At, B1); PG8_BAR; PG8_SCHED;
	s_add_i32 s63, 0, 0x18000
	s_add_i32 s64, 0, 0x1c000
	v_add_u32_e32 v142, s63, v163
	v_add_u32_e32 v158, s64, v163
	ds_read_b128 v[130:133], v142
	ds_read_b128 v[134:137], v142 offset:1024
	ds_read_b128 v[138:141], v142 offset:2048
	ds_read_b128 v[142:145], v142 offset:3072
	ds_read_b128 v[146:149], v158
	ds_read_b128 v[150:153], v158 offset:1024
	ds_read_b128 v[154:157], v158 offset:2048
	ds_read_b128 v[158:161], v158 offset:3072
	s_add_u32 s46, s46, 0x80000
	s_addc_u32 s47, s47, 0
	s_mov_b32 m0, s55
	v_lshl_add_u64 v[248:249], s[46:47], 0, v[186:187]
	ds_read_b128 v[192:195], v220 offset:32768
	ds_read_b128 v[196:199], v220 offset:33792
	ds_read_b128 v[222:225], v220 offset:34816
	ds_read_b128 v[226:229], v220 offset:35840
	ds_read_b128 v[230:233], v220 offset:36864
	ds_read_b128 v[234:237], v220 offset:37888
	ds_read_b128 v[238:241], v220 offset:38912
	ds_read_b128 v[242:245], v220 offset:39936
	global_load_lds_dwordx4 v[248:249], off
	v_lshl_add_u64 v[248:249], s[46:47], 0, v[182:183]
	s_mov_b32 m0, s56
	s_nop 0
	global_load_lds_dwordx4 v[248:249], off
	s_waitcnt vmcnt(8)
	s_waitcnt lgkmcnt(0)
	s_barrier
	s_setprio 0
	s_waitcnt lgkmcnt(0)
	v_mfma_f32_16x16x32_bf16 v[126:129], v[130:133], v[192:195], v[126:129]
	v_mfma_f32_16x16x32_bf16 v[122:125], v[138:141], v[192:195], v[122:125]
	v_mfma_f32_16x16x32_bf16 v[110:113], v[130:133], v[222:225], v[110:113]
	v_mfma_f32_16x16x32_bf16 v[106:109], v[138:141], v[222:225], v[106:109]
	v_mfma_f32_16x16x32_bf16 v[94:97], v[130:133], v[230:233], v[94:97]
	v_mfma_f32_16x16x32_bf16 v[90:93], v[138:141], v[230:233], v[90:93]
	v_mfma_f32_16x16x32_bf16 v[78:81], v[130:133], v[238:241], v[78:81]
	v_mfma_f32_16x16x32_bf16 v[74:77], v[138:141], v[238:241], v[74:77]
	v_mfma_f32_16x16x32_bf16 v[126:129], v[134:137], v[196:199], v[126:129]
	v_mfma_f32_16x16x32_bf16 v[122:125], v[142:145], v[196:199], v[122:125]
	v_mfma_f32_16x16x32_bf16 v[110:113], v[134:137], v[226:229], v[110:113]
	v_mfma_f32_16x16x32_bf16 v[106:109], v[142:145], v[226:229], v[106:109]
	v_mfma_f32_16x16x32_bf16 v[94:97], v[134:137], v[234:237], v[94:97]
	v_mfma_f32_16x16x32_bf16 v[90:93], v[142:145], v[234:237], v[90:93]
	v_mfma_f32_16x16x32_bf16 v[78:81], v[134:137], v[242:245], v[78:81]
	v_mfma_f32_16x16x32_bf16 v[74:77], v[142:145], v[242:245], v[74:77]
	s_setprio 1
	s_setprio 0
	v_mfma_f32_16x16x32_bf16 v[118:121], v[146:149], v[192:195], v[118:121]
	v_mfma_f32_16x16x32_bf16 v[114:117], v[154:157], v[192:195], v[114:117]
	v_mfma_f32_16x16x32_bf16 v[102:105], v[146:149], v[222:225], v[102:105]
	v_mfma_f32_16x16x32_bf16 v[98:101], v[154:157], v[222:225], v[98:101]
	v_mfma_f32_16x16x32_bf16 v[86:89], v[146:149], v[230:233], v[86:89]
	v_mfma_f32_16x16x32_bf16 v[82:85], v[154:157], v[230:233], v[82:85]
	v_mfma_f32_16x16x32_bf16 v[70:73], v[146:149], v[238:241], v[70:73]
	v_mfma_f32_16x16x32_bf16 v[66:69], v[154:157], v[238:241], v[66:69]
	v_mfma_f32_16x16x32_bf16 v[118:121], v[150:153], v[196:199], v[118:121]
	v_mfma_f32_16x16x32_bf16 v[114:117], v[158:161], v[196:199], v[114:117]
	v_mfma_f32_16x16x32_bf16 v[102:105], v[150:153], v[226:229], v[102:105]
	v_mfma_f32_16x16x32_bf16 v[98:101], v[158:161], v[226:229], v[98:101]
	v_mfma_f32_16x16x32_bf16 v[86:89], v[150:153], v[234:237], v[86:89]
	v_mfma_f32_16x16x32_bf16 v[82:85], v[158:161], v[234:237], v[82:85]
	v_mfma_f32_16x16x32_bf16 v[70:73], v[150:153], v[242:245], v[70:73]
	v_mfma_f32_16x16x32_bf16 v[66:69], v[158:161], v[242:245], v[66:69]
	s_setprio 1
	s_barrier
; #define PG8_STAGE(bufoff, gbase, voff) do { _Pragma("unroll") for (int _i = 0; _i < 2; ++_i) \
;         __builtin_amdgcn_global_load_lds((const unsigned*)((const char*)(gbase) + (voff)[_i]), (PG8_LAS unsigned*)(lds + (bufoff) + ldsw + _i * 8192), 16, 0, 0); } while (0)
; #define PG8_WAIT_V(n) asm volatile("s_waitcnt vmcnt(" #n ")" ::: "memory")
; #define PG8_WAIT_L(n) asm volatile("s_waitcnt lgkmcnt(" #n ")" ::: "memory")
; #define PG8_BAR __builtin_amdgcn_s_barrier()
; #define PG8_SCHED __builtin_amdgcn_sched_barrier(0)
; template <class Epi, class Sched, bool ALIGN_EPI = false, bool SP2 = false, bool FP8 = false>
; __device__ __forceinline__ void gemm_phase(PG8_LAS unsigned char* lds, const Gemm g, const Sched& S, const Epi& E, const int tid) {
;     ...
;             PG8_LDA(At, 1, 1); PG8_STAGE(PG8_SB(1, 0), b3, voffB); PG8_STAGE(PG8_SB(1, 1), b3 + hstepB, voffB); PG8_STAGE(PG8_SA(1, 0), a3, voffA);
;             PG8_WAIT_V(8); PG8_WAIT_L(0); PG8_BAR; PG8_MMA(1, 0, At, B0); PG8_MMA(1, 1, At, B1); PG8_BAR; PG8_SCHED;
	s_add_i32 s46, s63, s52
	v_lshl_add_u64 v[164:165], v[164:165], 0, s[38:39]
	s_mov_b32 m0, s46
	ds_read_b128 v[192:195], v220 offset:49152
	ds_read_b128 v[196:199], v220 offset:50176
	ds_read_b128 v[222:225], v220 offset:51200
	ds_read_b128 v[226:229], v220 offset:52224
	ds_read_b128 v[230:233], v220 offset:53248
	ds_read_b128 v[234:237], v220 offset:54272
	ds_read_b128 v[238:241], v220 offset:55296
	ds_read_b128 v[242:245], v220 offset:56320
	global_load_lds_dwordx4 v[164:165], off
	s_add_i32 m0, s46, 0x2000
	s_add_u32 s44, s44, 0x80080
	v_lshl_add_u64 v[164:165], v[166:167], 0, s[38:39]
	s_addc_u32 s45, s45, 0
	s_add_i32 s46, s64, s52
	global_load_lds_dwordx4 v[164:165], off
	v_lshl_add_u64 v[164:165], s[44:45], 0, v[184:185]
	s_mov_b32 m0, s46
	s_nop 0
	global_load_lds_dwordx4 v[164:165], off
	v_lshl_add_u64 v[164:165], s[44:45], 0, v[180:181]
	s_add_i32 m0, s46, 0x2000
	s_nop 0
	global_load_lds_dwordx4 v[164:165], off
	v_lshl_add_u64 v[164:165], v[200:201], 0, s[38:39]
	s_mov_b32 m0, s0
	s_nop 0
	global_load_lds_dwordx4 v[164:165], off
	v_lshl_add_u64 v[164:165], v[246:247], 0, s[38:39]
	s_mov_b32 m0, s57
	s_nop 0
	global_load_lds_dwordx4 v[164:165], off
	s_waitcnt vmcnt(8)
	s_waitcnt lgkmcnt(0)
	s_barrier
	s_setprio 0
	s_waitcnt lgkmcnt(0)
	v_mfma_f32_16x16x32_bf16 v[62:65], v[130:133], v[192:195], v[62:65]
	v_mfma_f32_16x16x32_bf16 v[58:61], v[138:141], v[192:195], v[58:61]
	v_mfma_f32_16x16x32_bf16 v[46:49], v[130:133], v[222:225], v[46:49]
	v_mfma_f32_16x16x32_bf16 v[42:45], v[138:141], v[222:225], v[42:45]
	v_mfma_f32_16x16x32_bf16 v[28:31], v[130:133], v[230:233], v[28:31]
	v_mfma_f32_16x16x32_bf16 v[24:27], v[138:141], v[230:233], v[24:27]
	v_mfma_f32_16x16x32_bf16 v[12:15], v[130:133], v[238:241], v[12:15]
	v_mfma_f32_16x16x32_bf16 v[8:11], v[138:141], v[238:241], v[8:11]
	v_mfma_f32_16x16x32_bf16 v[62:65], v[134:137], v[196:199], v[62:65]
	v_mfma_f32_16x16x32_bf16 v[58:61], v[142:145], v[196:199], v[58:61]
	v_mfma_f32_16x16x32_bf16 v[46:49], v[134:137], v[226:229], v[46:49]
	v_mfma_f32_16x16x32_bf16 v[42:45], v[142:145], v[226:229], v[42:45]
	v_mfma_f32_16x16x32_bf16 v[28:31], v[134:137], v[234:237], v[28:31]
	v_mfma_f32_16x16x32_bf16 v[24:27], v[142:145], v[234:237], v[24:27]
	v_mfma_f32_16x16x32_bf16 v[12:15], v[134:137], v[242:245], v[12:15]
	v_mfma_f32_16x16x32_bf16 v[8:11], v[142:145], v[242:245], v[8:11]
	s_setprio 1
	s_setprio 0
	v_mfma_f32_16x16x32_bf16 v[54:57], v[146:149], v[192:195], v[54:57]
	v_mfma_f32_16x16x32_bf16 v[50:53], v[154:157], v[192:195], v[50:53]
	v_mfma_f32_16x16x32_bf16 v[38:41], v[146:149], v[222:225], v[38:41]
	v_mfma_f32_16x16x32_bf16 v[34:37], v[154:157], v[222:225], v[34:37]
	v_mfma_f32_16x16x32_bf16 v[20:23], v[146:149], v[230:233], v[20:23]
	v_mfma_f32_16x16x32_bf16 v[16:19], v[154:157], v[230:233], v[16:19]
	v_mfma_f32_16x16x32_bf16 v[4:7], v[146:149], v[238:241], v[4:7]
	v_mfma_f32_16x16x32_bf16 v[0:3], v[154:157], v[238:241], v[0:3]
	v_mfma_f32_16x16x32_bf16 v[54:57], v[150:153], v[196:199], v[54:57]
	v_mfma_f32_16x16x32_bf16 v[50:53], v[158:161], v[196:199], v[50:53]
	v_mfma_f32_16x16x32_bf16 v[38:41], v[150:153], v[226:229], v[38:41]
	v_mfma_f32_16x16x32_bf16 v[34:37], v[158:161], v[226:229], v[34:37]
	v_mfma_f32_16x16x32_bf16 v[20:23], v[150:153], v[234:237], v[20:23]
	v_mfma_f32_16x16x32_bf16 v[16:19], v[158:161], v[234:237], v[16:19]
	v_mfma_f32_16x16x32_bf16 v[4:7], v[150:153], v[242:245], v[4:7]
	v_mfma_f32_16x16x32_bf16 v[0:3], v[158:161], v[242:245], v[0:3]
	s_setprio 1
	s_barrier
	s_add_i32 s62, s62, 2
	s_add_u32 s8, s8, 0x100
	s_addc_u32 s9, s9, 0
	s_add_u32 s60, s60, 0x100
	s_addc_u32 s61, s61, 0
	s_cmp_gt_u32 s62, 29
	s_cbranch_scc0 .LBB0_589
	s_setprio 0
	s_and_b64 vcc, exec, s[26:27]
	s_cbranch_vccz .LBB0_592
	s_barrier

; #define PG8_STAGE(bufoff, gbase, voff) do { _Pragma("unroll") for (int _i = 0; _i < 2; ++_i) \
;         __builtin_amdgcn_global_load_lds((const unsigned*)((const char*)(gbase) + (voff)[_i]), (PG8_LAS unsigned*)(lds + (bufoff) + ldsw + _i * 8192), 16, 0, 0); } while (0)
; #define PG8_WAIT_V(n) asm volatile("s_waitcnt vmcnt(" #n ")" ::: "memory")
; #define PG8_WAIT_L(n) asm volatile("s_waitcnt lgkmcnt(" #n ")" ::: "memory")
; #define PG8_BAR __builtin_amdgcn_s_barrier()
; #define PG8_SCHED __builtin_amdgcn_sched_barrier(0)
; template <class Epi, class Sched, bool ALIGN_EPI = false, bool SP2 = false, bool FP8 = false>
; __device__ __forceinline__ void gemm_phase(PG8_LAS unsigned char* lds, const Gemm g, const Sched& S, const Epi& E, const int tid) {
;     ...
;             PG8_WAIT_V(8); PG8_WAIT_L(0); PG8_BAR; PG8_MMA(0, 0, At, B0); PG8_MMA(0, 1, At, B1); PG8_BAR; PG8_SCHED;
;             PG8_LDA(At, 0, 1); PG8_STAGE(PG8_SB(0, 0), b2, voffB); PG8_STAGE(PG8_SB(0, 1), b2 + hstepB, voffB); PG8_STAGE(PG8_SA(0, 0), a2, voffA);
;             PG8_WAIT_V(8); PG8_WAIT_L(0); PG8_BAR; PG8_MMA(1, 0, At, B0); PG8_MMA(1, 1, At, B1); PG8_BAR; PG8_SCHED;
;             PG8_LDB(B0, 1, 0); PG8_LDB(B1, 1, 1); PG8_SCHED; PG8_LDA(At, 1, 0); PG8_STAGE(PG8_SA(0, 1), a2 + hstepA, voffA);
;             PG8_WAIT_V(8); PG8_WAIT_L(0); PG8_BAR; PG8_MMA(0, 0, At, B0); PG8_MMA(0, 1, At, B1); PG8_BAR; PG8_SCHED;
;             PG8_LDA(At, 1, 1); PG8_STAGE(PG8_SB(1, 0), b3, voffB); PG8_STAGE(PG8_SB(1, 1), b3 + hstepB, voffB); PG8_STAGE(PG8_SA(1, 0), a3, voffA);
.Lskw_4_0:
	s_waitcnt lgkmcnt(0)
	s_barrier
	s_setprio 0
	s_waitcnt lgkmcnt(0)
	v_mfma_f32_16x16x32_bf16 v[126:129], v[142:145], v[196:199], v[126:129]
	v_mfma_f32_16x16x32_bf16 v[122:125], v[154:157], v[196:199], v[122:125]
	v_mfma_f32_16x16x32_bf16 v[110:113], v[142:145], v[224:227], v[110:113]
	v_mfma_f32_16x16x32_bf16 v[106:109], v[154:157], v[224:227], v[106:109]
	v_mfma_f32_16x16x32_bf16 v[94:97], v[142:145], v[232:235], v[94:97]
	v_mfma_f32_16x16x32_bf16 v[90:93], v[154:157], v[232:235], v[90:93]
	v_mfma_f32_16x16x32_bf16 v[78:81], v[142:145], v[240:243], v[78:81]
	v_mfma_f32_16x16x32_bf16 v[74:77], v[154:157], v[240:243], v[74:77]
	v_mfma_f32_16x16x32_bf16 v[126:129], v[146:149], v[220:223], v[126:129]
	v_mfma_f32_16x16x32_bf16 v[122:125], v[158:161], v[220:223], v[122:125]
	v_mfma_f32_16x16x32_bf16 v[110:113], v[146:149], v[228:231], v[110:113]
	v_mfma_f32_16x16x32_bf16 v[106:109], v[158:161], v[228:231], v[106:109]
	v_mfma_f32_16x16x32_bf16 v[94:97], v[146:149], v[236:239], v[94:97]
	v_mfma_f32_16x16x32_bf16 v[90:93], v[158:161], v[236:239], v[90:93]
	v_mfma_f32_16x16x32_bf16 v[78:81], v[146:149], v[244:247], v[78:81]
	v_mfma_f32_16x16x32_bf16 v[74:77], v[158:161], v[244:247], v[74:77]
	s_setprio 1
	s_setprio 0
	v_mfma_f32_16x16x32_bf16 v[118:121], v[180:183], v[196:199], v[118:121]
	v_mfma_f32_16x16x32_bf16 v[114:117], v[188:191], v[196:199], v[114:117]
	v_mfma_f32_16x16x32_bf16 v[102:105], v[180:183], v[224:227], v[102:105]
	v_mfma_f32_16x16x32_bf16 v[98:101], v[188:191], v[224:227], v[98:101]
	v_mfma_f32_16x16x32_bf16 v[86:89], v[180:183], v[232:235], v[86:89]
	v_mfma_f32_16x16x32_bf16 v[82:85], v[188:191], v[232:235], v[82:85]
	v_mfma_f32_16x16x32_bf16 v[70:73], v[180:183], v[240:243], v[70:73]
	v_mfma_f32_16x16x32_bf16 v[66:69], v[188:191], v[240:243], v[66:69]
	v_mfma_f32_16x16x32_bf16 v[118:121], v[184:187], v[220:223], v[118:121]
	v_mfma_f32_16x16x32_bf16 v[114:117], v[192:195], v[220:223], v[114:117]
	v_mfma_f32_16x16x32_bf16 v[102:105], v[184:187], v[228:231], v[102:105]
	v_mfma_f32_16x16x32_bf16 v[98:101], v[192:195], v[228:231], v[98:101]
	v_mfma_f32_16x16x32_bf16 v[86:89], v[184:187], v[236:239], v[86:89]
	v_mfma_f32_16x16x32_bf16 v[82:85], v[192:195], v[236:239], v[82:85]
	v_mfma_f32_16x16x32_bf16 v[70:73], v[184:187], v[244:247], v[70:73]
	v_mfma_f32_16x16x32_bf16 v[66:69], v[192:195], v[244:247], v[66:69]
	s_setprio 1
	s_barrier
	s_add_i32 s57, s57, s46
	v_lshl_add_u64 v[164:165], s[34:35], 0, v[134:135]
	s_mov_b32 m0, s57
	ds_read_b128 v[196:199], v152 offset:16384
	ds_read_b128 v[220:223], v152 offset:17408
	ds_read_b128 v[224:227], v152 offset:18432
	ds_read_b128 v[228:231], v152 offset:19456
	ds_read_b128 v[232:235], v152 offset:20480
	ds_read_b128 v[236:239], v152 offset:21504
	ds_read_b128 v[240:243], v152 offset:22528
	ds_read_b128 v[244:247], v152 offset:23552
	global_load_lds_dwordx4 v[164:165], off
	s_add_i32 m0, s57, 0x2000
	s_add_u32 s58, s34, 0x80000
	v_lshl_add_u64 v[166:167], s[34:35], 0, v[130:131]
	s_addc_u32 s59, s35, 0
	s_add_i32 s57, s60, s46
	global_load_lds_dwordx4 v[166:167], off
	v_lshl_add_u64 v[200:201], s[58:59], 0, v[134:135]
	s_mov_b32 m0, s57
	v_lshl_add_u64 v[248:249], s[36:37], 0, v[132:133]
	global_load_lds_dwordx4 v[200:201], off
	v_lshl_add_u64 v[200:201], s[58:59], 0, v[130:131]
	s_add_i32 m0, s57, 0x2000
	s_nop 0
	global_load_lds_dwordx4 v[200:201], off
	v_lshl_add_u64 v[200:201], s[36:37], 0, v[136:137]
	s_mov_b32 m0, s47
	s_nop 0
	global_load_lds_dwordx4 v[200:201], off
	s_mov_b32 m0, s48
	s_nop 0
	global_load_lds_dwordx4 v[248:249], off
	s_cmp_eq_i32 s56, -2
	s_cbranch_scc1 .Lskw_4_1
	s_waitcnt vmcnt(8)
.Lskw_4_1:
	s_waitcnt lgkmcnt(0)
	s_barrier
	s_setprio 0
	s_waitcnt lgkmcnt(0)
	v_mfma_f32_16x16x32_bf16 v[62:65], v[142:145], v[196:199], v[62:65]
	v_mfma_f32_16x16x32_bf16 v[58:61], v[154:157], v[196:199], v[58:61]
	v_mfma_f32_16x16x32_bf16 v[46:49], v[142:145], v[224:227], v[46:49]
	v_mfma_f32_16x16x32_bf16 v[42:45], v[154:157], v[224:227], v[42:45]
	v_mfma_f32_16x16x32_bf16 v[28:31], v[142:145], v[232:235], v[28:31]
	v_mfma_f32_16x16x32_bf16 v[24:27], v[154:157], v[232:235], v[24:27]
	v_mfma_f32_16x16x32_bf16 v[12:15], v[142:145], v[240:243], v[12:15]
	v_mfma_f32_16x16x32_bf16 v[8:11], v[154:157], v[240:243], v[8:11]
	v_mfma_f32_16x16x32_bf16 v[62:65], v[146:149], v[220:223], v[62:65]
	v_mfma_f32_16x16x32_bf16 v[58:61], v[158:161], v[220:223], v[58:61]
	v_mfma_f32_16x16x32_bf16 v[46:49], v[146:149], v[228:231], v[46:49]
	v_mfma_f32_16x16x32_bf16 v[42:45], v[158:161], v[228:231], v[42:45]
	v_mfma_f32_16x16x32_bf16 v[28:31], v[146:149], v[236:239], v[28:31]
	v_mfma_f32_16x16x32_bf16 v[24:27], v[158:161], v[236:239], v[24:27]
	v_mfma_f32_16x16x32_bf16 v[12:15], v[146:149], v[244:247], v[12:15]
	v_mfma_f32_16x16x32_bf16 v[8:11], v[158:161], v[244:247], v[8:11]
	s_setprio 1
	s_setprio 0
	v_mfma_f32_16x16x32_bf16 v[54:57], v[180:183], v[196:199], v[54:57]
	v_mfma_f32_16x16x32_bf16 v[50:53], v[188:191], v[196:199], v[50:53]
	v_mfma_f32_16x16x32_bf16 v[38:41], v[180:183], v[224:227], v[38:41]
	v_mfma_f32_16x16x32_bf16 v[34:37], v[188:191], v[224:227], v[34:37]
	v_mfma_f32_16x16x32_bf16 v[20:23], v[180:183], v[232:235], v[20:23]
	v_mfma_f32_16x16x32_bf16 v[16:19], v[188:191], v[232:235], v[16:19]
	v_mfma_f32_16x16x32_bf16 v[4:7], v[180:183], v[240:243], v[4:7]
	v_mfma_f32_16x16x32_bf16 v[0:3], v[188:191], v[240:243], v[0:3]
	v_mfma_f32_16x16x32_bf16 v[54:57], v[184:187], v[220:223], v[54:57]
	v_mfma_f32_16x16x32_bf16 v[50:53], v[192:195], v[220:223], v[50:53]
	v_mfma_f32_16x16x32_bf16 v[38:41], v[184:187], v[228:231], v[38:41]
	v_mfma_f32_16x16x32_bf16 v[34:37], v[192:195], v[228:231], v[34:37]
	v_mfma_f32_16x16x32_bf16 v[20:23], v[184:187], v[236:239], v[20:23]
	v_mfma_f32_16x16x32_bf16 v[16:19], v[192:195], v[236:239], v[16:19]
	v_mfma_f32_16x16x32_bf16 v[4:7], v[184:187], v[244:247], v[4:7]
	v_mfma_f32_16x16x32_bf16 v[0:3], v[192:195], v[244:247], v[0:3]
	s_setprio 1
	s_barrier
; #define PG8_STAGE(bufoff, gbase, voff) do { _Pragma("unroll") for (int _i = 0; _i < 2; ++_i) \
;         __builtin_amdgcn_global_load_lds((const unsigned*)((const char*)(gbase) + (voff)[_i]), (PG8_LAS unsigned*)(lds + (bufoff) + ldsw + _i * 8192), 16, 0, 0); } while (0)
; #define PG8_WAIT_V(n) asm volatile("s_waitcnt vmcnt(" #n ")" ::: "memory")
; #define PG8_WAIT_L(n) asm volatile("s_waitcnt lgkmcnt(" #n ")" ::: "memory")
; #define PG8_BAR __builtin_amdgcn_s_barrier()
; #define PG8_SCHED __builtin_amdgcn_sched_barrier(0)
; template <class Epi, class Sched, bool ALIGN_EPI = false, bool SP2 = false, bool FP8 = false>
; __device__ __forceinline__ void gemm_phase(PG8_LAS unsigned char* lds, const Gemm g, const Sched& S, const Epi& E, const int tid) {
;     ...
;             PG8_LDB(B0, 1, 0); PG8_LDB(B1, 1, 1); PG8_SCHED; PG8_LDA(At, 1, 0); PG8_STAGE(PG8_SA(0, 1), a2 + hstepA, voffA);
;             PG8_WAIT_V(8); PG8_WAIT_L(0); PG8_BAR; PG8_MMA(0, 0, At, B0); PG8_MMA(0, 1, At, B1); PG8_BAR; PG8_SCHED;
	s_add_i32 s57, 0, 0x18000
	v_add_u32_e32 v153, s57, v150
	s_add_i32 s58, 0, 0x1c000
	ds_read_b128 v[142:145], v153
	ds_read_b128 v[146:149], v153 offset:1024
	ds_read_b128 v[154:157], v153 offset:2048
	ds_read_b128 v[158:161], v153 offset:3072
	v_add_u32_e32 v153, s58, v150
	ds_read_b128 v[180:183], v153
	ds_read_b128 v[184:187], v153 offset:1024
	ds_read_b128 v[188:191], v153 offset:2048
	ds_read_b128 v[192:195], v153 offset:3072
	s_add_u32 s36, s36, 0x80000
	s_addc_u32 s37, s37, 0
	s_mov_b32 m0, s49
	v_lshl_add_u64 v[250:251], s[36:37], 0, v[136:137]
	ds_read_b128 v[196:199], v152 offset:32768
	ds_read_b128 v[220:223], v152 offset:33792
	ds_read_b128 v[224:227], v152 offset:34816
	ds_read_b128 v[228:231], v152 offset:35840
	ds_read_b128 v[232:235], v152 offset:36864
	ds_read_b128 v[236:239], v152 offset:37888
	ds_read_b128 v[240:243], v152 offset:38912
	ds_read_b128 v[244:247], v152 offset:39936
	global_load_lds_dwordx4 v[250:251], off
	v_lshl_add_u64 v[250:251], s[36:37], 0, v[132:133]
	s_mov_b32 m0, s50
	s_nop 0
	global_load_lds_dwordx4 v[250:251], off
	s_waitcnt vmcnt(8)
	s_waitcnt lgkmcnt(0)
	s_barrier
	s_setprio 0
	s_waitcnt lgkmcnt(0)
	v_mfma_f32_16x16x32_bf16 v[126:129], v[142:145], v[196:199], v[126:129]
	v_mfma_f32_16x16x32_bf16 v[122:125], v[154:157], v[196:199], v[122:125]
	v_mfma_f32_16x16x32_bf16 v[110:113], v[142:145], v[224:227], v[110:113]
	v_mfma_f32_16x16x32_bf16 v[106:109], v[154:157], v[224:227], v[106:109]
	v_mfma_f32_16x16x32_bf16 v[94:97], v[142:145], v[232:235], v[94:97]
	v_mfma_f32_16x16x32_bf16 v[90:93], v[154:157], v[232:235], v[90:93]
	v_mfma_f32_16x16x32_bf16 v[78:81], v[142:145], v[240:243], v[78:81]
	v_mfma_f32_16x16x32_bf16 v[74:77], v[154:157], v[240:243], v[74:77]
	v_mfma_f32_16x16x32_bf16 v[126:129], v[146:149], v[220:223], v[126:129]
	v_mfma_f32_16x16x32_bf16 v[122:125], v[158:161], v[220:223], v[122:125]
	v_mfma_f32_16x16x32_bf16 v[110:113], v[146:149], v[228:231], v[110:113]
	v_mfma_f32_16x16x32_bf16 v[106:109], v[158:161], v[228:231], v[106:109]
	v_mfma_f32_16x16x32_bf16 v[94:97], v[146:149], v[236:239], v[94:97]
	v_mfma_f32_16x16x32_bf16 v[90:93], v[158:161], v[236:239], v[90:93]
	v_mfma_f32_16x16x32_bf16 v[78:81], v[146:149], v[244:247], v[78:81]
	v_mfma_f32_16x16x32_bf16 v[74:77], v[158:161], v[244:247], v[74:77]
	s_setprio 1
	s_setprio 0
	v_mfma_f32_16x16x32_bf16 v[118:121], v[180:183], v[196:199], v[118:121]
	v_mfma_f32_16x16x32_bf16 v[114:117], v[188:191], v[196:199], v[114:117]
	v_mfma_f32_16x16x32_bf16 v[102:105], v[180:183], v[224:227], v[102:105]
	v_mfma_f32_16x16x32_bf16 v[98:101], v[188:191], v[224:227], v[98:101]
	v_mfma_f32_16x16x32_bf16 v[86:89], v[180:183], v[232:235], v[86:89]
	v_mfma_f32_16x16x32_bf16 v[82:85], v[188:191], v[232:235], v[82:85]
	v_mfma_f32_16x16x32_bf16 v[70:73], v[180:183], v[240:243], v[70:73]
	v_mfma_f32_16x16x32_bf16 v[66:69], v[188:191], v[240:243], v[66:69]
	v_mfma_f32_16x16x32_bf16 v[118:121], v[184:187], v[220:223], v[118:121]
	v_mfma_f32_16x16x32_bf16 v[114:117], v[192:195], v[220:223], v[114:117]
	v_mfma_f32_16x16x32_bf16 v[102:105], v[184:187], v[228:231], v[102:105]
	v_mfma_f32_16x16x32_bf16 v[98:101], v[192:195], v[228:231], v[98:101]
	v_mfma_f32_16x16x32_bf16 v[86:89], v[184:187], v[236:239], v[86:89]
	v_mfma_f32_16x16x32_bf16 v[82:85], v[192:195], v[236:239], v[82:85]
	v_mfma_f32_16x16x32_bf16 v[70:73], v[184:187], v[244:247], v[70:73]
	v_mfma_f32_16x16x32_bf16 v[66:69], v[192:195], v[244:247], v[66:69]
	s_setprio 1
	s_barrier
; #define PG8_STAGE(bufoff, gbase, voff) do { _Pragma("unroll") for (int _i = 0; _i < 2; ++_i) \
;         __builtin_amdgcn_global_load_lds((const unsigned*)((const char*)(gbase) + (voff)[_i]), (PG8_LAS unsigned*)(lds + (bufoff) + ldsw + _i * 8192), 16, 0, 0); } while (0)
; #define PG8_WAIT_V(n) asm volatile("s_waitcnt vmcnt(" #n ")" ::: "memory")
; #define PG8_WAIT_L(n) asm volatile("s_waitcnt lgkmcnt(" #n ")" ::: "memory")
; #define PG8_BAR __builtin_amdgcn_s_barrier()
; #define PG8_SCHED __builtin_amdgcn_sched_barrier(0)
;     __device__ __forceinline__ void operator()(const f32x4 (&acc)[2][2][4][2], const Unit& u, int wr, int wc, int fr, int fq) const {
;     ...
;             for (int m = 0; m < 4; ++m) { const int row = row0 + ai * HALF + m * 16; const float rs = __builtin_amdgcn_rsqf((float)ss[row] * (SS_INV / 2048.0f) + RMS_EPS) * osc;
; template <class Epi, class Sched, bool ALIGN_EPI = false, bool SP2 = false, bool FP8 = false>
; __device__ __forceinline__ void gemm_phase(PG8_LAS unsigned char* lds, const Gemm g, const Sched& S, const Epi& E, const int tid) {
;     ...
;             PG8_LDA(At, 1, 1); PG8_STAGE(PG8_SB(1, 0), b3, voffB); PG8_STAGE(PG8_SB(1, 1), b3 + hstepB, voffB); PG8_STAGE(PG8_SA(1, 0), a3, voffA);
;             PG8_WAIT_V(8); PG8_WAIT_L(0); PG8_BAR; PG8_MMA(1, 0, At, B0); PG8_MMA(1, 1, At, B1); PG8_BAR; PG8_SCHED;
;     ...
;         if constexpr (ALIGN_EPI) { if (wr == 0) PG8_BAR; }
	s_add_i32 s36, s57, s46
	v_lshl_add_u64 v[164:165], v[164:165], 0, s[38:39]
	s_mov_b32 m0, s36
	ds_read_b128 v[196:199], v152 offset:49152
	ds_read_b128 v[220:223], v152 offset:50176
	ds_read_b128 v[224:227], v152 offset:51200
	ds_read_b128 v[228:231], v152 offset:52224
	ds_read_b128 v[232:235], v152 offset:53248
	ds_read_b128 v[236:239], v152 offset:54272
	ds_read_b128 v[240:243], v152 offset:55296
	ds_read_b128 v[244:247], v152 offset:56320
	global_load_lds_dwordx4 v[164:165], off
	s_add_i32 m0, s36, 0x2000
	s_add_u32 s34, s34, 0x80080
	v_lshl_add_u64 v[164:165], v[166:167], 0, s[38:39]
	s_addc_u32 s35, s35, 0
	s_add_i32 s36, s58, s46
	global_load_lds_dwordx4 v[164:165], off
	v_lshl_add_u64 v[164:165], s[34:35], 0, v[134:135]
	s_mov_b32 m0, s36
	s_nop 0
	global_load_lds_dwordx4 v[164:165], off
	v_lshl_add_u64 v[164:165], s[34:35], 0, v[130:131]
	s_add_i32 m0, s36, 0x2000
	s_nop 0
	global_load_lds_dwordx4 v[164:165], off
	v_lshl_add_u64 v[164:165], v[200:201], 0, s[38:39]
	s_mov_b32 m0, s0
	s_nop 0
	global_load_lds_dwordx4 v[164:165], off
	v_lshl_add_u64 v[164:165], v[248:249], 0, s[38:39]
	s_mov_b32 m0, s51
	s_nop 0
	global_load_lds_dwordx4 v[164:165], off
	s_waitcnt vmcnt(8)
	s_waitcnt lgkmcnt(0)
	s_barrier
	s_setprio 0
	s_waitcnt lgkmcnt(0)
	v_mfma_f32_16x16x32_bf16 v[62:65], v[142:145], v[196:199], v[62:65]
	v_mfma_f32_16x16x32_bf16 v[58:61], v[154:157], v[196:199], v[58:61]
	v_mfma_f32_16x16x32_bf16 v[46:49], v[142:145], v[224:227], v[46:49]
	v_mfma_f32_16x16x32_bf16 v[42:45], v[154:157], v[224:227], v[42:45]
	v_mfma_f32_16x16x32_bf16 v[28:31], v[142:145], v[232:235], v[28:31]
	v_mfma_f32_16x16x32_bf16 v[24:27], v[154:157], v[232:235], v[24:27]
	v_mfma_f32_16x16x32_bf16 v[12:15], v[142:145], v[240:243], v[12:15]
	v_mfma_f32_16x16x32_bf16 v[8:11], v[154:157], v[240:243], v[8:11]
	v_mfma_f32_16x16x32_bf16 v[62:65], v[146:149], v[220:223], v[62:65]
	v_mfma_f32_16x16x32_bf16 v[58:61], v[158:161], v[220:223], v[58:61]
	v_mfma_f32_16x16x32_bf16 v[46:49], v[146:149], v[228:231], v[46:49]
	v_mfma_f32_16x16x32_bf16 v[42:45], v[158:161], v[228:231], v[42:45]
	v_mfma_f32_16x16x32_bf16 v[28:31], v[146:149], v[236:239], v[28:31]
	v_mfma_f32_16x16x32_bf16 v[24:27], v[158:161], v[236:239], v[24:27]
	v_mfma_f32_16x16x32_bf16 v[12:15], v[146:149], v[244:247], v[12:15]
	v_mfma_f32_16x16x32_bf16 v[8:11], v[158:161], v[244:247], v[8:11]
	s_setprio 1
	s_setprio 0
	v_mfma_f32_16x16x32_bf16 v[54:57], v[180:183], v[196:199], v[54:57]
	v_mfma_f32_16x16x32_bf16 v[50:53], v[188:191], v[196:199], v[50:53]
	v_mfma_f32_16x16x32_bf16 v[38:41], v[180:183], v[224:227], v[38:41]
	v_mfma_f32_16x16x32_bf16 v[34:37], v[188:191], v[224:227], v[34:37]
	v_mfma_f32_16x16x32_bf16 v[20:23], v[180:183], v[232:235], v[20:23]
	v_mfma_f32_16x16x32_bf16 v[16:19], v[188:191], v[232:235], v[16:19]
	v_mfma_f32_16x16x32_bf16 v[4:7], v[180:183], v[240:243], v[4:7]
	v_mfma_f32_16x16x32_bf16 v[0:3], v[188:191], v[240:243], v[0:3]
	v_mfma_f32_16x16x32_bf16 v[54:57], v[184:187], v[220:223], v[54:57]
	v_mfma_f32_16x16x32_bf16 v[50:53], v[192:195], v[220:223], v[50:53]
	v_mfma_f32_16x16x32_bf16 v[38:41], v[184:187], v[228:231], v[38:41]
	v_mfma_f32_16x16x32_bf16 v[34:37], v[192:195], v[228:231], v[34:37]
	v_mfma_f32_16x16x32_bf16 v[20:23], v[184:187], v[236:239], v[20:23]
	v_mfma_f32_16x16x32_bf16 v[16:19], v[192:195], v[236:239], v[16:19]
	v_mfma_f32_16x16x32_bf16 v[4:7], v[184:187], v[244:247], v[4:7]
	v_mfma_f32_16x16x32_bf16 v[0:3], v[192:195], v[244:247], v[0:3]
	s_setprio 1
	s_barrier
	s_add_i32 s56, s56, 2
	s_add_u32 s30, s30, 0x100
	s_addc_u32 s31, s31, 0
	s_add_u32 s54, s54, 0x100
	s_addc_u32 s55, s55, 0
	s_cmp_gt_u32 s56, 29
	s_cbranch_scc0 .LBB0_735
	s_setprio 0
	v_lshl_add_u32 v148, s22, 8, v33
	v_ashrrev_i32_e32 v149, 31, v148
	v_lshl_add_u64 v[144:145], v[148:149], 3, s[12:13]
	global_load_dwordx2 v[220:221], v[144:145], off
	global_load_dwordx2 v[222:223], v[144:145], off offset:128
	global_load_dwordx2 v[224:225], v[144:145], off offset:256
	global_load_dwordx2 v[226:227], v[144:145], off offset:384
	global_load_dwordx2 v[228:229], v[144:145], off offset:1024
	global_load_dwordx2 v[230:231], v[144:145], off offset:1152
	global_load_dwordx2 v[232:233], v[144:145], off offset:1280
	global_load_dwordx2 v[234:235], v[144:145], off offset:1408
	s_and_b64 vcc, exec, s[14:15]
	s_cbranch_vccz .LBB0_738
	s_barrier

; #define PG8_STAGE(bufoff, gbase, voff) do { _Pragma("unroll") for (int _i = 0; _i < 2; ++_i) \
;         __builtin_amdgcn_global_load_lds((const unsigned*)((const char*)(gbase) + (voff)[_i]), (PG8_LAS unsigned*)(lds + (bufoff) + ldsw + _i * 8192), 16, 0, 0); } while (0)
; #define PG8_WAIT_V(n) asm volatile("s_waitcnt vmcnt(" #n ")" ::: "memory")
; #define PG8_WAIT_L(n) asm volatile("s_waitcnt lgkmcnt(" #n ")" ::: "memory")
; #define PG8_BAR __builtin_amdgcn_s_barrier()
; #define PG8_SCHED __builtin_amdgcn_sched_barrier(0)
; template <class Epi, class Sched, bool ALIGN_EPI = false, bool SP2 = false, bool FP8 = false>
; __device__ __forceinline__ void gemm_phase(PG8_LAS unsigned char* lds, const Gemm g, const Sched& S, const Epi& E, const int tid) {
;     ...
;             PG8_WAIT_V(8); PG8_WAIT_L(0); PG8_BAR; PG8_MMA(0, 0, At, B0); PG8_MMA(0, 1, At, B1); PG8_BAR; PG8_SCHED;
;             PG8_LDA(At, 0, 1); PG8_STAGE(PG8_SB(0, 0), b2, voffB); PG8_STAGE(PG8_SB(0, 1), b2 + hstepB, voffB); PG8_STAGE(PG8_SA(0, 0), a2, voffA);
;             PG8_WAIT_V(8); PG8_WAIT_L(0); PG8_BAR; PG8_MMA(1, 0, At, B0); PG8_MMA(1, 1, At, B1); PG8_BAR; PG8_SCHED;
.Lskw_5_0:
	s_waitcnt lgkmcnt(0)
	s_barrier
	s_setprio 0
	s_waitcnt lgkmcnt(0)
	v_mfma_f32_16x16x32_bf16 v[126:129], v[130:133], v[194:197], v[126:129]
	v_mfma_f32_16x16x32_bf16 v[122:125], v[138:141], v[194:197], v[122:125]
	v_mfma_f32_16x16x32_bf16 v[110:113], v[130:133], v[220:223], v[110:113]
	v_mfma_f32_16x16x32_bf16 v[106:109], v[138:141], v[220:223], v[106:109]
	v_mfma_f32_16x16x32_bf16 v[94:97], v[130:133], v[228:231], v[94:97]
	v_mfma_f32_16x16x32_bf16 v[90:93], v[138:141], v[228:231], v[90:93]
	v_mfma_f32_16x16x32_bf16 v[78:81], v[130:133], v[236:239], v[78:81]
	v_mfma_f32_16x16x32_bf16 v[74:77], v[138:141], v[236:239], v[74:77]
	v_mfma_f32_16x16x32_bf16 v[126:129], v[134:137], v[198:201], v[126:129]
	v_mfma_f32_16x16x32_bf16 v[122:125], v[154:157], v[198:201], v[122:125]
	v_mfma_f32_16x16x32_bf16 v[110:113], v[134:137], v[224:227], v[110:113]
	v_mfma_f32_16x16x32_bf16 v[106:109], v[154:157], v[224:227], v[106:109]
	v_mfma_f32_16x16x32_bf16 v[94:97], v[134:137], v[232:235], v[94:97]
	v_mfma_f32_16x16x32_bf16 v[90:93], v[154:157], v[232:235], v[90:93]
	v_mfma_f32_16x16x32_bf16 v[78:81], v[134:137], v[240:243], v[78:81]
	v_mfma_f32_16x16x32_bf16 v[74:77], v[154:157], v[240:243], v[74:77]
	s_setprio 1
	s_setprio 0
	v_mfma_f32_16x16x32_bf16 v[118:121], v[158:161], v[194:197], v[118:121]
	v_mfma_f32_16x16x32_bf16 v[114:117], v[184:187], v[194:197], v[114:117]
	v_mfma_f32_16x16x32_bf16 v[102:105], v[158:161], v[220:223], v[102:105]
	v_mfma_f32_16x16x32_bf16 v[98:101], v[184:187], v[220:223], v[98:101]
	v_mfma_f32_16x16x32_bf16 v[86:89], v[158:161], v[228:231], v[86:89]
	v_mfma_f32_16x16x32_bf16 v[82:85], v[184:187], v[228:231], v[82:85]
	v_mfma_f32_16x16x32_bf16 v[70:73], v[158:161], v[236:239], v[70:73]
	v_mfma_f32_16x16x32_bf16 v[66:69], v[184:187], v[236:239], v[66:69]
	v_mfma_f32_16x16x32_bf16 v[118:121], v[180:183], v[198:201], v[118:121]
	v_mfma_f32_16x16x32_bf16 v[114:117], v[190:193], v[198:201], v[114:117]
	v_mfma_f32_16x16x32_bf16 v[102:105], v[180:183], v[224:227], v[102:105]
	v_mfma_f32_16x16x32_bf16 v[98:101], v[190:193], v[224:227], v[98:101]
	v_mfma_f32_16x16x32_bf16 v[86:89], v[180:183], v[232:235], v[86:89]
	v_mfma_f32_16x16x32_bf16 v[82:85], v[190:193], v[232:235], v[82:85]
	v_mfma_f32_16x16x32_bf16 v[70:73], v[180:183], v[240:243], v[70:73]
	v_mfma_f32_16x16x32_bf16 v[66:69], v[190:193], v[240:243], v[66:69]
	s_setprio 1
	s_barrier
	s_add_i32 s63, s63, s51
	v_lshl_add_u64 v[164:165], s[10:11], 0, v[146:147]
	s_mov_b32 m0, s63
	ds_read_b128 v[194:197], v188 offset:16384
	ds_read_b128 v[198:201], v188 offset:17408
	ds_read_b128 v[220:223], v188 offset:18432
	ds_read_b128 v[224:227], v188 offset:19456
	ds_read_b128 v[228:231], v188 offset:20480
	ds_read_b128 v[232:235], v188 offset:21504
	ds_read_b128 v[236:239], v188 offset:22528
	ds_read_b128 v[240:243], v188 offset:23552
	global_load_lds_dwordx4 v[164:165], off
	s_add_i32 m0, s63, 0x2000
	s_add_u32 s64, s10, 0x200000
	v_lshl_add_u64 v[166:167], s[10:11], 0, v[142:143]
	s_addc_u32 s65, s11, 0
	s_add_i32 s63, s66, s51
	global_load_lds_dwordx4 v[166:167], off
	v_lshl_add_u64 v[244:245], s[64:65], 0, v[146:147]
	s_mov_b32 m0, s63
	v_lshl_add_u64 v[246:247], s[46:47], 0, v[144:145]
	global_load_lds_dwordx4 v[244:245], off
	v_lshl_add_u64 v[244:245], s[64:65], 0, v[142:143]
	s_add_i32 m0, s63, 0x2000
	s_nop 0
	global_load_lds_dwordx4 v[244:245], off
	v_lshl_add_u64 v[244:245], s[46:47], 0, v[148:149]
	s_mov_b32 m0, s52
	s_nop 0
	global_load_lds_dwordx4 v[244:245], off
	s_mov_b32 m0, s53
	s_nop 0
	global_load_lds_dwordx4 v[246:247], off
	s_cmp_eq_i32 s62, -2
	s_cbranch_scc1 .Lskw_5_1
	s_waitcnt vmcnt(8)
.Lskw_5_1:
	s_waitcnt lgkmcnt(0)
	s_barrier
	s_setprio 0
	s_waitcnt lgkmcnt(0)
	v_mfma_f32_16x16x32_bf16 v[62:65], v[130:133], v[194:197], v[62:65]
	v_mfma_f32_16x16x32_bf16 v[58:61], v[138:141], v[194:197], v[58:61]
	v_mfma_f32_16x16x32_bf16 v[46:49], v[130:133], v[220:223], v[46:49]
	v_mfma_f32_16x16x32_bf16 v[42:45], v[138:141], v[220:223], v[42:45]
	v_mfma_f32_16x16x32_bf16 v[28:31], v[130:133], v[228:231], v[28:31]
	v_mfma_f32_16x16x32_bf16 v[24:27], v[138:141], v[228:231], v[24:27]
	v_mfma_f32_16x16x32_bf16 v[12:15], v[130:133], v[236:239], v[12:15]
	v_mfma_f32_16x16x32_bf16 v[8:11], v[138:141], v[236:239], v[8:11]
	v_mfma_f32_16x16x32_bf16 v[62:65], v[134:137], v[198:201], v[62:65]
	v_mfma_f32_16x16x32_bf16 v[58:61], v[154:157], v[198:201], v[58:61]
	v_mfma_f32_16x16x32_bf16 v[46:49], v[134:137], v[224:227], v[46:49]
	v_mfma_f32_16x16x32_bf16 v[42:45], v[154:157], v[224:227], v[42:45]
	v_mfma_f32_16x16x32_bf16 v[28:31], v[134:137], v[232:235], v[28:31]
	v_mfma_f32_16x16x32_bf16 v[24:27], v[154:157], v[232:235], v[24:27]
	v_mfma_f32_16x16x32_bf16 v[12:15], v[134:137], v[240:243], v[12:15]
	v_mfma_f32_16x16x32_bf16 v[8:11], v[154:157], v[240:243], v[8:11]
	s_setprio 1
	s_setprio 0
	v_mfma_f32_16x16x32_bf16 v[54:57], v[158:161], v[194:197], v[54:57]
	v_mfma_f32_16x16x32_bf16 v[50:53], v[184:187], v[194:197], v[50:53]
	v_mfma_f32_16x16x32_bf16 v[38:41], v[158:161], v[220:223], v[38:41]
	v_mfma_f32_16x16x32_bf16 v[34:37], v[184:187], v[220:223], v[34:37]
	v_mfma_f32_16x16x32_bf16 v[20:23], v[158:161], v[228:231], v[20:23]
	v_mfma_f32_16x16x32_bf16 v[16:19], v[184:187], v[228:231], v[16:19]
	v_mfma_f32_16x16x32_bf16 v[4:7], v[158:161], v[236:239], v[4:7]
	v_mfma_f32_16x16x32_bf16 v[0:3], v[184:187], v[236:239], v[0:3]
	v_mfma_f32_16x16x32_bf16 v[54:57], v[180:183], v[198:201], v[54:57]
	v_mfma_f32_16x16x32_bf16 v[50:53], v[190:193], v[198:201], v[50:53]
	v_mfma_f32_16x16x32_bf16 v[38:41], v[180:183], v[224:227], v[38:41]
	v_mfma_f32_16x16x32_bf16 v[34:37], v[190:193], v[224:227], v[34:37]
	v_mfma_f32_16x16x32_bf16 v[20:23], v[180:183], v[232:235], v[20:23]
	v_mfma_f32_16x16x32_bf16 v[16:19], v[190:193], v[232:235], v[16:19]
	v_mfma_f32_16x16x32_bf16 v[4:7], v[180:183], v[240:243], v[4:7]
	v_mfma_f32_16x16x32_bf16 v[0:3], v[190:193], v[240:243], v[0:3]
	s_setprio 1
	s_barrier
; #define PG8_STAGE(bufoff, gbase, voff) do { _Pragma("unroll") for (int _i = 0; _i < 2; ++_i) \
;         __builtin_amdgcn_global_load_lds((const unsigned*)((const char*)(gbase) + (voff)[_i]), (PG8_LAS unsigned*)(lds + (bufoff) + ldsw + _i * 8192), 16, 0, 0); } while (0)
; #define PG8_WAIT_V(n) asm volatile("s_waitcnt vmcnt(" #n ")" ::: "memory")
; #define PG8_WAIT_L(n) asm volatile("s_waitcnt lgkmcnt(" #n ")" ::: "memory")
; #define PG8_BAR __builtin_amdgcn_s_barrier()
; #define PG8_SCHED __builtin_amdgcn_sched_barrier(0)
; template <class Epi, class Sched, bool ALIGN_EPI = false, bool SP2 = false, bool FP8 = false>
; __device__ __forceinline__ void gemm_phase(PG8_LAS unsigned char* lds, const Gemm g, const Sched& S, const Epi& E, const int tid) {
;     ...
;             PG8_LDB(B0, 1, 0); PG8_LDB(B1, 1, 1); PG8_SCHED; PG8_LDA(At, 1, 0); PG8_STAGE(PG8_SA(0, 1), a2 + hstepA, voffA);
;             PG8_WAIT_V(8); PG8_WAIT_L(0); PG8_BAR; PG8_MMA(0, 0, At, B0); PG8_MMA(0, 1, At, B1); PG8_BAR; PG8_SCHED;
	s_add_i32 s63, 0, 0x18000
	s_add_i32 s64, 0, 0x1c000
	v_add_u32_e32 v154, s63, v163
	v_add_u32_e32 v189, s64, v163
	ds_read_b128 v[130:133], v154
	ds_read_b128 v[134:137], v154 offset:1024
	ds_read_b128 v[138:141], v154 offset:2048
	ds_read_b128 v[154:157], v154 offset:3072
	ds_read_b128 v[158:161], v189
	ds_read_b128 v[180:183], v189 offset:1024
	ds_read_b128 v[184:187], v189 offset:2048
	ds_read_b128 v[190:193], v189 offset:3072
	s_add_u32 s46, s46, 0x200000
	s_addc_u32 s47, s47, 0
	s_mov_b32 m0, s54
	v_lshl_add_u64 v[248:249], s[46:47], 0, v[148:149]
	ds_read_b128 v[194:197], v188 offset:32768
	ds_read_b128 v[198:201], v188 offset:33792
	ds_read_b128 v[220:223], v188 offset:34816
	ds_read_b128 v[224:227], v188 offset:35840
	ds_read_b128 v[228:231], v188 offset:36864
	ds_read_b128 v[232:235], v188 offset:37888
	ds_read_b128 v[236:239], v188 offset:38912
	ds_read_b128 v[240:243], v188 offset:39936
	global_load_lds_dwordx4 v[248:249], off
	v_lshl_add_u64 v[248:249], s[46:47], 0, v[144:145]
	s_mov_b32 m0, s55
	s_nop 0
	global_load_lds_dwordx4 v[248:249], off
	s_waitcnt vmcnt(8)
	s_waitcnt lgkmcnt(0)
	s_barrier
	s_setprio 0
	s_waitcnt lgkmcnt(0)
	v_mfma_f32_16x16x32_bf16 v[126:129], v[130:133], v[194:197], v[126:129]
	v_mfma_f32_16x16x32_bf16 v[122:125], v[138:141], v[194:197], v[122:125]
	v_mfma_f32_16x16x32_bf16 v[110:113], v[130:133], v[220:223], v[110:113]
	v_mfma_f32_16x16x32_bf16 v[106:109], v[138:141], v[220:223], v[106:109]
	v_mfma_f32_16x16x32_bf16 v[94:97], v[130:133], v[228:231], v[94:97]
	v_mfma_f32_16x16x32_bf16 v[90:93], v[138:141], v[228:231], v[90:93]
	v_mfma_f32_16x16x32_bf16 v[78:81], v[130:133], v[236:239], v[78:81]
	v_mfma_f32_16x16x32_bf16 v[74:77], v[138:141], v[236:239], v[74:77]
	v_mfma_f32_16x16x32_bf16 v[126:129], v[134:137], v[198:201], v[126:129]
	v_mfma_f32_16x16x32_bf16 v[122:125], v[154:157], v[198:201], v[122:125]
	v_mfma_f32_16x16x32_bf16 v[110:113], v[134:137], v[224:227], v[110:113]
	v_mfma_f32_16x16x32_bf16 v[106:109], v[154:157], v[224:227], v[106:109]
	v_mfma_f32_16x16x32_bf16 v[94:97], v[134:137], v[232:235], v[94:97]
	v_mfma_f32_16x16x32_bf16 v[90:93], v[154:157], v[232:235], v[90:93]
	v_mfma_f32_16x16x32_bf16 v[78:81], v[134:137], v[240:243], v[78:81]
	v_mfma_f32_16x16x32_bf16 v[74:77], v[154:157], v[240:243], v[74:77]
	s_setprio 1
	s_setprio 0
	v_mfma_f32_16x16x32_bf16 v[118:121], v[158:161], v[194:197], v[118:121]
	v_mfma_f32_16x16x32_bf16 v[114:117], v[184:187], v[194:197], v[114:117]
	v_mfma_f32_16x16x32_bf16 v[102:105], v[158:161], v[220:223], v[102:105]
	v_mfma_f32_16x16x32_bf16 v[98:101], v[184:187], v[220:223], v[98:101]
	v_mfma_f32_16x16x32_bf16 v[86:89], v[158:161], v[228:231], v[86:89]
	v_mfma_f32_16x16x32_bf16 v[82:85], v[184:187], v[228:231], v[82:85]
	v_mfma_f32_16x16x32_bf16 v[70:73], v[158:161], v[236:239], v[70:73]
	v_mfma_f32_16x16x32_bf16 v[66:69], v[184:187], v[236:239], v[66:69]
	v_mfma_f32_16x16x32_bf16 v[118:121], v[180:183], v[198:201], v[118:121]
	v_mfma_f32_16x16x32_bf16 v[114:117], v[190:193], v[198:201], v[114:117]
	v_mfma_f32_16x16x32_bf16 v[102:105], v[180:183], v[224:227], v[102:105]
	v_mfma_f32_16x16x32_bf16 v[98:101], v[190:193], v[224:227], v[98:101]
	v_mfma_f32_16x16x32_bf16 v[86:89], v[180:183], v[232:235], v[86:89]
	v_mfma_f32_16x16x32_bf16 v[82:85], v[190:193], v[232:235], v[82:85]
	v_mfma_f32_16x16x32_bf16 v[70:73], v[180:183], v[240:243], v[70:73]
	v_mfma_f32_16x16x32_bf16 v[66:69], v[190:193], v[240:243], v[66:69]
	s_setprio 1
	s_barrier
; #define PG8_STAGE(bufoff, gbase, voff) do { _Pragma("unroll") for (int _i = 0; _i < 2; ++_i) \
;         __builtin_amdgcn_global_load_lds((const unsigned*)((const char*)(gbase) + (voff)[_i]), (PG8_LAS unsigned*)(lds + (bufoff) + ldsw + _i * 8192), 16, 0, 0); } while (0)
; #define PG8_WAIT_V(n) asm volatile("s_waitcnt vmcnt(" #n ")" ::: "memory")
; #define PG8_WAIT_L(n) asm volatile("s_waitcnt lgkmcnt(" #n ")" ::: "memory")
; #define PG8_BAR __builtin_amdgcn_s_barrier()
; #define PG8_SCHED __builtin_amdgcn_sched_barrier(0)
; template <class Epi, class Sched, bool ALIGN_EPI = false, bool SP2 = false, bool FP8 = false>
; __device__ __forceinline__ void gemm_phase(PG8_LAS unsigned char* lds, const Gemm g, const Sched& S, const Epi& E, const int tid) {
;     ...
;             PG8_LDA(At, 1, 1); PG8_STAGE(PG8_SB(1, 0), b3, voffB); PG8_STAGE(PG8_SB(1, 1), b3 + hstepB, voffB); PG8_STAGE(PG8_SA(1, 0), a3, voffA);
;             PG8_WAIT_V(8); PG8_WAIT_L(0); PG8_BAR; PG8_MMA(1, 0, At, B0); PG8_MMA(1, 1, At, B1); PG8_BAR; PG8_SCHED;
;     ...
;         if constexpr (ALIGN_EPI) { if (wr == 0) PG8_BAR; }
	s_add_i32 s46, s63, s51
	v_lshl_add_u64 v[164:165], v[164:165], 0, s[38:39]
	s_mov_b32 m0, s46
	ds_read_b128 v[194:197], v188 offset:49152
	ds_read_b128 v[198:201], v188 offset:50176
	ds_read_b128 v[220:223], v188 offset:51200
	ds_read_b128 v[224:227], v188 offset:52224
	ds_read_b128 v[228:231], v188 offset:53248
	ds_read_b128 v[232:235], v188 offset:54272
	ds_read_b128 v[236:239], v188 offset:55296
	ds_read_b128 v[240:243], v188 offset:56320
	global_load_lds_dwordx4 v[164:165], off
	s_add_i32 m0, s46, 0x2000
	s_add_u32 s10, s10, 0x200080
	v_lshl_add_u64 v[164:165], v[166:167], 0, s[38:39]
	s_addc_u32 s11, s11, 0
	s_add_i32 s46, s64, s51
	global_load_lds_dwordx4 v[164:165], off
	v_lshl_add_u64 v[164:165], s[10:11], 0, v[146:147]
	s_mov_b32 m0, s46
	s_nop 0
	global_load_lds_dwordx4 v[164:165], off
	v_lshl_add_u64 v[164:165], s[10:11], 0, v[142:143]
	s_add_i32 m0, s46, 0x2000
	s_nop 0
	global_load_lds_dwordx4 v[164:165], off
	v_lshl_add_u64 v[164:165], v[244:245], 0, s[38:39]
	s_mov_b32 m0, s56
	s_nop 0
	global_load_lds_dwordx4 v[164:165], off
	v_lshl_add_u64 v[164:165], v[246:247], 0, s[38:39]
	s_mov_b32 m0, s57
	s_nop 0
	global_load_lds_dwordx4 v[164:165], off
	s_waitcnt vmcnt(8)
	s_waitcnt lgkmcnt(0)
	s_barrier
	s_setprio 0
	s_waitcnt lgkmcnt(0)
	v_mfma_f32_16x16x32_bf16 v[62:65], v[130:133], v[194:197], v[62:65]
	v_mfma_f32_16x16x32_bf16 v[58:61], v[138:141], v[194:197], v[58:61]
	v_mfma_f32_16x16x32_bf16 v[46:49], v[130:133], v[220:223], v[46:49]
	v_mfma_f32_16x16x32_bf16 v[42:45], v[138:141], v[220:223], v[42:45]
	v_mfma_f32_16x16x32_bf16 v[28:31], v[130:133], v[228:231], v[28:31]
	v_mfma_f32_16x16x32_bf16 v[24:27], v[138:141], v[228:231], v[24:27]
	v_mfma_f32_16x16x32_bf16 v[12:15], v[130:133], v[236:239], v[12:15]
	v_mfma_f32_16x16x32_bf16 v[8:11], v[138:141], v[236:239], v[8:11]
	v_mfma_f32_16x16x32_bf16 v[62:65], v[134:137], v[198:201], v[62:65]
	v_mfma_f32_16x16x32_bf16 v[58:61], v[154:157], v[198:201], v[58:61]
	v_mfma_f32_16x16x32_bf16 v[46:49], v[134:137], v[224:227], v[46:49]
	v_mfma_f32_16x16x32_bf16 v[42:45], v[154:157], v[224:227], v[42:45]
	v_mfma_f32_16x16x32_bf16 v[28:31], v[134:137], v[232:235], v[28:31]
	v_mfma_f32_16x16x32_bf16 v[24:27], v[154:157], v[232:235], v[24:27]
	v_mfma_f32_16x16x32_bf16 v[12:15], v[134:137], v[240:243], v[12:15]
	v_mfma_f32_16x16x32_bf16 v[8:11], v[154:157], v[240:243], v[8:11]
	s_setprio 1
	s_setprio 0
	v_mfma_f32_16x16x32_bf16 v[54:57], v[158:161], v[194:197], v[54:57]
	v_mfma_f32_16x16x32_bf16 v[50:53], v[184:187], v[194:197], v[50:53]
	v_mfma_f32_16x16x32_bf16 v[38:41], v[158:161], v[220:223], v[38:41]
	v_mfma_f32_16x16x32_bf16 v[34:37], v[184:187], v[220:223], v[34:37]
	v_mfma_f32_16x16x32_bf16 v[20:23], v[158:161], v[228:231], v[20:23]
	v_mfma_f32_16x16x32_bf16 v[16:19], v[184:187], v[228:231], v[16:19]
	v_mfma_f32_16x16x32_bf16 v[4:7], v[158:161], v[236:239], v[4:7]
	v_mfma_f32_16x16x32_bf16 v[0:3], v[184:187], v[236:239], v[0:3]
	v_mfma_f32_16x16x32_bf16 v[54:57], v[180:183], v[198:201], v[54:57]
	v_mfma_f32_16x16x32_bf16 v[50:53], v[190:193], v[198:201], v[50:53]
	v_mfma_f32_16x16x32_bf16 v[38:41], v[180:183], v[224:227], v[38:41]
	v_mfma_f32_16x16x32_bf16 v[34:37], v[190:193], v[224:227], v[34:37]
	v_mfma_f32_16x16x32_bf16 v[20:23], v[180:183], v[232:235], v[20:23]
	v_mfma_f32_16x16x32_bf16 v[16:19], v[190:193], v[232:235], v[16:19]
	v_mfma_f32_16x16x32_bf16 v[4:7], v[180:183], v[240:243], v[4:7]
	v_mfma_f32_16x16x32_bf16 v[0:3], v[190:193], v[240:243], v[0:3]
	s_setprio 1
	s_barrier
	s_add_i32 s62, s62, 2
	s_add_u32 s8, s8, 0x100
	s_addc_u32 s9, s9, 0
	s_add_u32 s60, s60, 0x100
	s_addc_u32 s61, s61, 0
	s_cmpk_gt_u32 s62, 0x7d
	s_cbranch_scc0 .LBB0_801
	s_setprio 0
	s_and_b64 vcc, exec, s[30:31]
	s_cbranch_vccz .LBB0_804
	s_barrier
